# v29 + nt cache hint on the SwiGLU GEMM output stores (write-once stream)
# baseline (speedup 1.0000x reference)
; #define PG8_STAGE(bufoff, gbase, voff) do { _Pragma("unroll") for (int _i = 0; _i < 2; ++_i) \
;         __builtin_amdgcn_global_load_lds((const unsigned*)((const char*)(gbase) + (voff)[_i]), (LAS unsigned*)(lds + (bufoff) + ldsw + _i * 8192), 16, 0, 0); } while (0)
; #define PG8_LDA(dst, b, h) do { _Pragma("unroll") for (int m = 0; m < 4; ++m) _Pragma("unroll") for (int k = 0; k < 2; ++k) dst[m][k] = *(const LAS bf16x8*)(lds + PG8_SA(b, h) + aoff + m * 2048 + k * 1024); } while (0)
; #define PG8_LDB(dst, b, h) do { _Pragma("unroll") for (int n = 0; n < 2; ++n) _Pragma("unroll") for (int k = 0; k < 2; ++k) dst[n][k] = *(const LAS bf16x8*)(lds + PG8_SB(b, h) + boff + n * 2048 + k * 1024); } while (0)
; #define PG8_MMA(ai, bj, At, Bt) do { __builtin_amdgcn_s_setprio(1); _Pragma("unroll") for (int m = 0; m < 4; ++m) _Pragma("unroll") for (int n = 0; n < 2; ++n) _Pragma("unroll") for (int k = 0; k < 2; ++k) \
;         acc[ai][bj][m][n] = __builtin_amdgcn_mfma_f32_16x16x32_bf16(Bt[n][k], At[m][k], acc[ai][bj][m][n], 0, 0, 0); __builtin_amdgcn_s_setprio(0); } while (0)
; #define PG8_WAIT_L(n) asm volatile("s_waitcnt lgkmcnt(" #n ")" ::: "memory")
; #define PG8_BAR __builtin_amdgcn_s_barrier()
; #define PG8_SCHED __builtin_amdgcn_sched_barrier(0)
; template <class Epi>
; __device__ __forceinline__ void gemm_phase(LAS unsigned char* lds, const Gemm g, const Sched& S, const Epi& E) {
;     ...
;             PG8_LDB(B0, 0, 0); PG8_SCHED; PG8_LDA(At, 0, 0); PG8_STAGE(PG8_SA(1, 1), a1 + hstepA, voffA);
;             PG8_WAIT_L(8); PG8_BAR; PG8_WAIT_L(0); PG8_MMA(0, 0, At, B0); PG8_BAR; PG8_SCHED;
;             PG8_LDB(B1, 0, 1); PG8_STAGE(PG8_SB(0, 0), b2, voffB);
;             PG8_BAR; PG8_WAIT_L(0); PG8_MMA(0, 1, At, B1); PG8_BAR;
;             PG8_LDA(At, 0, 1); PG8_STAGE(PG8_SA(0, 0), a2, voffA);
;             PG8_BAR; PG8_WAIT_L(0); PG8_MMA(1, 0, At, B0); PG8_BAR; PG8_SCHED;
.LBB0_177:
	v_add_u32_e32 v162, s62, v148
	s_add_u32 s38, s10, s24
	ds_read_b128 v[150:153], v162
	ds_read_b128 v[154:157], v162 offset:1024
	ds_read_b128 v[158:161], v162 offset:2048
	ds_read_b128 v[162:165], v162 offset:3072
	s_addc_u32 s39, s11, s25
	s_add_u32 s38, s38, 0x100
	s_addc_u32 s39, s39, 0
	s_add_u32 s71, s9, s24
	s_addc_u32 s80, s51, s25
	s_cmpk_eq_i32 s24, 0xf00
	s_cselect_b32 s53, s19, s39
	s_cselect_b32 s52, s66, s38
	s_cselect_b32 s39, s17, s80
	s_cselect_b32 s38, s67, s71
	v_lshl_add_u64 v[190:191], v[144:145], 0, s[24:25]
	s_add_i32 m0, s35, 0xc000
	ds_read_b128 v[166:169], v149
	ds_read_b128 v[170:173], v149 offset:1024
	ds_read_b128 v[174:177], v149 offset:2048
	ds_read_b128 v[178:181], v149 offset:3072
	ds_read_b128 v[182:185], v149 offset:4096
	ds_read_b128 v[186:189], v149 offset:5120
	ds_read_b128 v[194:197], v149 offset:6144
	ds_read_b128 v[198:201], v149 offset:7168
	global_load_lds_dwordx4 v[190:191], off
	v_lshl_add_u64 v[190:191], v[146:147], 0, s[24:25]
	s_add_i32 m0, s35, 0xe000
	s_nop 0
	global_load_lds_dwordx4 v[190:191], off
	s_waitcnt lgkmcnt(8)
	s_barrier
	s_waitcnt lgkmcnt(0)
	s_setprio 1
	s_waitcnt lgkmcnt(0)
	v_mfma_f32_16x16x32_bf16 v[124:127], v[150:153], v[166:169], v[124:127]
	v_mfma_f32_16x16x32_bf16 v[120:123], v[158:161], v[166:169], v[120:123]
	v_mfma_f32_16x16x32_bf16 v[116:119], v[150:153], v[174:177], v[116:119]
	v_mfma_f32_16x16x32_bf16 v[112:115], v[158:161], v[174:177], v[112:115]
	v_mfma_f32_16x16x32_bf16 v[108:111], v[150:153], v[182:185], v[108:111]
	v_mfma_f32_16x16x32_bf16 v[104:107], v[158:161], v[182:185], v[104:107]
	v_mfma_f32_16x16x32_bf16 v[100:103], v[150:153], v[194:197], v[100:103]
	v_mfma_f32_16x16x32_bf16 v[96:99], v[158:161], v[194:197], v[96:99]
	v_mfma_f32_16x16x32_bf16 v[124:127], v[154:157], v[170:173], v[124:127]
	v_mfma_f32_16x16x32_bf16 v[120:123], v[162:165], v[170:173], v[120:123]
	v_mfma_f32_16x16x32_bf16 v[116:119], v[154:157], v[178:181], v[116:119]
	v_mfma_f32_16x16x32_bf16 v[112:115], v[162:165], v[178:181], v[112:115]
	v_mfma_f32_16x16x32_bf16 v[108:111], v[154:157], v[186:189], v[108:111]
	v_mfma_f32_16x16x32_bf16 v[104:107], v[162:165], v[186:189], v[104:107]
	v_mfma_f32_16x16x32_bf16 v[100:103], v[154:157], v[198:201], v[100:103]
	v_mfma_f32_16x16x32_bf16 v[96:99], v[162:165], v[198:201], v[96:99]
	s_setprio 0
	s_barrier
	v_add_u32_e32 v190, s63, v148
	s_add_i32 s71, s62, s1
	ds_read_b128 v[202:205], v190
	ds_read_b128 v[206:209], v190 offset:1024
	ds_read_b128 v[210:213], v190 offset:2048
	ds_read_b128 v[214:217], v190 offset:3072
	v_lshl_add_u64 v[190:191], s[38:39], 0, v[130:131]
	s_mov_b32 m0, s71
	v_lshl_add_u64 v[218:219], s[38:39], 0, v[128:129]
	global_load_lds_dwordx4 v[190:191], off
	s_add_i32 m0, s71, 0x2000
	s_nop 0
	global_load_lds_dwordx4 v[218:219], off
	s_barrier
	s_waitcnt lgkmcnt(0)
	s_setprio 1
	s_waitcnt lgkmcnt(0)
	v_mfma_f32_16x16x32_bf16 v[92:95], v[202:205], v[166:169], v[92:95]
	v_mfma_f32_16x16x32_bf16 v[88:91], v[210:213], v[166:169], v[88:91]
	v_mfma_f32_16x16x32_bf16 v[84:87], v[202:205], v[174:177], v[84:87]
	v_mfma_f32_16x16x32_bf16 v[80:83], v[210:213], v[174:177], v[80:83]
	v_mfma_f32_16x16x32_bf16 v[76:79], v[202:205], v[182:185], v[76:79]
	v_mfma_f32_16x16x32_bf16 v[72:75], v[210:213], v[182:185], v[72:75]
	v_mfma_f32_16x16x32_bf16 v[68:71], v[202:205], v[194:197], v[68:71]
	v_mfma_f32_16x16x32_bf16 v[64:67], v[210:213], v[194:197], v[64:67]
	v_mfma_f32_16x16x32_bf16 v[92:95], v[206:209], v[170:173], v[92:95]
	v_mfma_f32_16x16x32_bf16 v[88:91], v[214:217], v[170:173], v[88:91]
	v_mfma_f32_16x16x32_bf16 v[84:87], v[206:209], v[178:181], v[84:87]
	v_mfma_f32_16x16x32_bf16 v[80:83], v[214:217], v[178:181], v[80:83]
	v_mfma_f32_16x16x32_bf16 v[76:79], v[206:209], v[186:189], v[76:79]
	v_mfma_f32_16x16x32_bf16 v[72:75], v[214:217], v[186:189], v[72:75]
	v_mfma_f32_16x16x32_bf16 v[68:71], v[206:209], v[198:201], v[68:71]
	v_mfma_f32_16x16x32_bf16 v[64:67], v[214:217], v[198:201], v[64:67]
	s_setprio 0
	s_mov_b32 m0, s35
	v_lshl_add_u64 v[220:221], s[52:53], 0, v[130:131]
	s_barrier
	ds_read_b128 v[166:169], v149 offset:16384
	ds_read_b128 v[170:173], v149 offset:17408
	ds_read_b128 v[174:177], v149 offset:18432
	ds_read_b128 v[178:181], v149 offset:19456
	ds_read_b128 v[182:185], v149 offset:20480
	ds_read_b128 v[186:189], v149 offset:21504
	ds_read_b128 v[194:197], v149 offset:22528
	ds_read_b128 v[198:201], v149 offset:23552
	global_load_lds_dwordx4 v[220:221], off
	v_lshl_add_u64 v[222:223], s[52:53], 0, v[128:129]
	s_mov_b32 m0, s43
	s_nop 0
	global_load_lds_dwordx4 v[222:223], off
	s_barrier
	s_waitcnt lgkmcnt(0)
	s_setprio 1
	s_waitcnt lgkmcnt(0)
	v_mfma_f32_16x16x32_bf16 v[60:63], v[150:153], v[166:169], v[60:63]
	v_mfma_f32_16x16x32_bf16 v[56:59], v[158:161], v[166:169], v[56:59]
	v_mfma_f32_16x16x32_bf16 v[52:55], v[150:153], v[174:177], v[52:55]
	v_mfma_f32_16x16x32_bf16 v[48:51], v[158:161], v[174:177], v[48:51]
	v_mfma_f32_16x16x32_bf16 v[44:47], v[150:153], v[182:185], v[44:47]
	v_mfma_f32_16x16x32_bf16 v[40:43], v[158:161], v[182:185], v[40:43]
	v_mfma_f32_16x16x32_bf16 v[36:39], v[150:153], v[194:197], v[36:39]
	v_mfma_f32_16x16x32_bf16 v[32:35], v[158:161], v[194:197], v[32:35]
	v_mfma_f32_16x16x32_bf16 v[60:63], v[154:157], v[170:173], v[60:63]
	v_mfma_f32_16x16x32_bf16 v[56:59], v[162:165], v[170:173], v[56:59]
	v_mfma_f32_16x16x32_bf16 v[52:55], v[154:157], v[178:181], v[52:55]
	v_mfma_f32_16x16x32_bf16 v[48:51], v[162:165], v[178:181], v[48:51]
	v_mfma_f32_16x16x32_bf16 v[44:47], v[154:157], v[186:189], v[44:47]
	v_mfma_f32_16x16x32_bf16 v[40:43], v[162:165], v[186:189], v[40:43]
	v_mfma_f32_16x16x32_bf16 v[36:39], v[154:157], v[198:201], v[36:39]
	v_mfma_f32_16x16x32_bf16 v[32:35], v[162:165], v[198:201], v[32:35]
	s_setprio 0
	s_barrier
; #define PG8_STAGE(bufoff, gbase, voff) do { _Pragma("unroll") for (int _i = 0; _i < 2; ++_i) \
;         __builtin_amdgcn_global_load_lds((const unsigned*)((const char*)(gbase) + (voff)[_i]), (LAS unsigned*)(lds + (bufoff) + ldsw + _i * 8192), 16, 0, 0); } while (0)
; #define PG8_LDA(dst, b, h) do { _Pragma("unroll") for (int m = 0; m < 4; ++m) _Pragma("unroll") for (int k = 0; k < 2; ++k) dst[m][k] = *(const LAS bf16x8*)(lds + PG8_SA(b, h) + aoff + m * 2048 + k * 1024); } while (0)
; #define PG8_LDB(dst, b, h) do { _Pragma("unroll") for (int n = 0; n < 2; ++n) _Pragma("unroll") for (int k = 0; k < 2; ++k) dst[n][k] = *(const LAS bf16x8*)(lds + PG8_SB(b, h) + boff + n * 2048 + k * 1024); } while (0)
; #define PG8_MMA(ai, bj, At, Bt) do { __builtin_amdgcn_s_setprio(1); _Pragma("unroll") for (int m = 0; m < 4; ++m) _Pragma("unroll") for (int n = 0; n < 2; ++n) _Pragma("unroll") for (int k = 0; k < 2; ++k) \
;         acc[ai][bj][m][n] = __builtin_amdgcn_mfma_f32_16x16x32_bf16(Bt[n][k], At[m][k], acc[ai][bj][m][n], 0, 0, 0); __builtin_amdgcn_s_setprio(0); } while (0)
; #define PG8_WAIT_V(n) asm volatile("s_waitcnt vmcnt(" #n ")" ::: "memory")
; #define PG8_WAIT_L(n) asm volatile("s_waitcnt lgkmcnt(" #n ")" ::: "memory")
; #define PG8_BAR __builtin_amdgcn_s_barrier()
; #define PG8_SCHED __builtin_amdgcn_sched_barrier(0)
; template <class Epi>
; __device__ __forceinline__ void gemm_phase(LAS unsigned char* lds, const Gemm g, const Sched& S, const Epi& E) {
;     ...
;             PG8_STAGE(PG8_SB(0, 1), b2 + hstepB, voffB);
;             PG8_WAIT_V(6); PG8_BAR; PG8_MMA(1, 1, At, B1); PG8_BAR;
;             PG8_LDB(B0, 1, 0); PG8_SCHED; PG8_LDA(At, 1, 0); PG8_STAGE(PG8_SA(0, 1), a2 + hstepA, voffA);
;             PG8_WAIT_L(8); PG8_BAR; PG8_WAIT_L(0); PG8_MMA(0, 0, At, B0); PG8_BAR; PG8_SCHED;
;             PG8_LDB(B1, 1, 1); PG8_STAGE(PG8_SB(1, 0), b3, voffB);
;             PG8_BAR; PG8_WAIT_L(0); PG8_MMA(0, 1, At, B1); PG8_BAR;
;             PG8_LDA(At, 1, 1); PG8_STAGE(PG8_SA(1, 0), a3, voffA);
	s_add_u32 s80, s38, 0x80000
	s_addc_u32 s81, s39, 0
	s_add_i32 s71, s63, s1
	v_lshl_add_u64 v[150:151], s[80:81], 0, v[130:131]
	s_mov_b32 m0, s71
	s_nop 0
	global_load_lds_dwordx4 v[150:151], off
	v_lshl_add_u64 v[150:151], s[80:81], 0, v[128:129]
	s_add_i32 m0, s71, 0x2000
	s_nop 0
	global_load_lds_dwordx4 v[150:151], off
	s_waitcnt vmcnt(6)
	s_barrier
	s_setprio 1
	v_mfma_f32_16x16x32_bf16 v[28:31], v[202:205], v[166:169], v[28:31]
	v_mfma_f32_16x16x32_bf16 v[24:27], v[210:213], v[166:169], v[24:27]
	v_mfma_f32_16x16x32_bf16 v[20:23], v[202:205], v[174:177], v[20:23]
	v_mfma_f32_16x16x32_bf16 v[16:19], v[210:213], v[174:177], v[16:19]
	v_mfma_f32_16x16x32_bf16 v[12:15], v[202:205], v[182:185], v[12:15]
	v_mfma_f32_16x16x32_bf16 v[8:11], v[210:213], v[182:185], v[8:11]
	v_mfma_f32_16x16x32_bf16 v[4:7], v[202:205], v[194:197], v[4:7]
	v_mfma_f32_16x16x32_bf16 v[0:3], v[210:213], v[194:197], v[0:3]
	v_mfma_f32_16x16x32_bf16 v[28:31], v[206:209], v[170:173], v[28:31]
	v_mfma_f32_16x16x32_bf16 v[24:27], v[214:217], v[170:173], v[24:27]
	v_mfma_f32_16x16x32_bf16 v[20:23], v[206:209], v[178:181], v[20:23]
	v_mfma_f32_16x16x32_bf16 v[16:19], v[214:217], v[178:181], v[16:19]
	v_mfma_f32_16x16x32_bf16 v[12:15], v[206:209], v[186:189], v[12:15]
	v_mfma_f32_16x16x32_bf16 v[8:11], v[214:217], v[186:189], v[8:11]
	v_mfma_f32_16x16x32_bf16 v[4:7], v[206:209], v[198:201], v[4:7]
	v_mfma_f32_16x16x32_bf16 v[0:3], v[214:217], v[198:201], v[0:3]
	s_setprio 0
	s_add_i32 s71, 0, 0x18000
	v_add_u32_e32 v162, s71, v148
	s_barrier
	ds_read_b128 v[150:153], v162
	ds_read_b128 v[154:157], v162 offset:1024
	ds_read_b128 v[158:161], v162 offset:2048
	ds_read_b128 v[162:165], v162 offset:3072
	s_add_u32 s52, s52, 0x80000
	s_addc_u32 s53, s53, 0
	s_mov_b32 m0, s54
	v_lshl_add_u64 v[202:203], s[52:53], 0, v[130:131]
	ds_read_b128 v[166:169], v149 offset:32768
	ds_read_b128 v[170:173], v149 offset:33792
	ds_read_b128 v[174:177], v149 offset:34816
	ds_read_b128 v[178:181], v149 offset:35840
	ds_read_b128 v[182:185], v149 offset:36864
	ds_read_b128 v[186:189], v149 offset:37888
	ds_read_b128 v[194:197], v149 offset:38912
	ds_read_b128 v[198:201], v149 offset:39936
	global_load_lds_dwordx4 v[202:203], off
	v_lshl_add_u64 v[202:203], s[52:53], 0, v[128:129]
	s_mov_b32 m0, s55
	s_nop 0
	global_load_lds_dwordx4 v[202:203], off
	s_waitcnt lgkmcnt(8)
	s_barrier
	s_waitcnt lgkmcnt(0)
	s_setprio 1
	s_waitcnt lgkmcnt(0)
	v_mfma_f32_16x16x32_bf16 v[124:127], v[150:153], v[166:169], v[124:127]
	v_mfma_f32_16x16x32_bf16 v[120:123], v[158:161], v[166:169], v[120:123]
	v_mfma_f32_16x16x32_bf16 v[116:119], v[150:153], v[174:177], v[116:119]
	v_mfma_f32_16x16x32_bf16 v[112:115], v[158:161], v[174:177], v[112:115]
	v_mfma_f32_16x16x32_bf16 v[108:111], v[150:153], v[182:185], v[108:111]
	v_mfma_f32_16x16x32_bf16 v[104:107], v[158:161], v[182:185], v[104:107]
	v_mfma_f32_16x16x32_bf16 v[100:103], v[150:153], v[194:197], v[100:103]
	v_mfma_f32_16x16x32_bf16 v[96:99], v[158:161], v[194:197], v[96:99]
	v_mfma_f32_16x16x32_bf16 v[124:127], v[154:157], v[170:173], v[124:127]
	v_mfma_f32_16x16x32_bf16 v[120:123], v[162:165], v[170:173], v[120:123]
	v_mfma_f32_16x16x32_bf16 v[116:119], v[154:157], v[178:181], v[116:119]
	v_mfma_f32_16x16x32_bf16 v[112:115], v[162:165], v[178:181], v[112:115]
	v_mfma_f32_16x16x32_bf16 v[108:111], v[154:157], v[186:189], v[108:111]
	v_mfma_f32_16x16x32_bf16 v[104:107], v[162:165], v[186:189], v[104:107]
	v_mfma_f32_16x16x32_bf16 v[100:103], v[154:157], v[198:201], v[100:103]
	v_mfma_f32_16x16x32_bf16 v[96:99], v[162:165], v[198:201], v[96:99]
	s_setprio 0
	s_barrier
	s_add_i32 s52, 0, 0x1c000
	s_add_i32 s53, s71, s1
	v_add_u32_e32 v214, s52, v148
	v_lshl_add_u64 v[190:191], v[190:191], 0, s[14:15]
	s_mov_b32 m0, s53
	ds_read_b128 v[202:205], v214
	ds_read_b128 v[206:209], v214 offset:1024
	ds_read_b128 v[210:213], v214 offset:2048
	ds_read_b128 v[214:217], v214 offset:3072
	global_load_lds_dwordx4 v[190:191], off
	v_lshl_add_u64 v[190:191], v[218:219], 0, s[14:15]
	s_add_i32 m0, s53, 0x2000
	s_nop 0
	global_load_lds_dwordx4 v[190:191], off
	s_barrier
	s_waitcnt lgkmcnt(0)
	s_setprio 1
	s_waitcnt lgkmcnt(0)
	v_mfma_f32_16x16x32_bf16 v[92:95], v[202:205], v[166:169], v[92:95]
	v_mfma_f32_16x16x32_bf16 v[88:91], v[210:213], v[166:169], v[88:91]
	v_mfma_f32_16x16x32_bf16 v[84:87], v[202:205], v[174:177], v[84:87]
	v_mfma_f32_16x16x32_bf16 v[80:83], v[210:213], v[174:177], v[80:83]
	v_mfma_f32_16x16x32_bf16 v[76:79], v[202:205], v[182:185], v[76:79]
	v_mfma_f32_16x16x32_bf16 v[72:75], v[210:213], v[182:185], v[72:75]
	v_mfma_f32_16x16x32_bf16 v[68:71], v[202:205], v[194:197], v[68:71]
	v_mfma_f32_16x16x32_bf16 v[64:67], v[210:213], v[194:197], v[64:67]
	v_mfma_f32_16x16x32_bf16 v[92:95], v[206:209], v[170:173], v[92:95]
	v_mfma_f32_16x16x32_bf16 v[88:91], v[214:217], v[170:173], v[88:91]
	v_mfma_f32_16x16x32_bf16 v[84:87], v[206:209], v[178:181], v[84:87]
	v_mfma_f32_16x16x32_bf16 v[80:83], v[214:217], v[178:181], v[80:83]
	v_mfma_f32_16x16x32_bf16 v[76:79], v[206:209], v[186:189], v[76:79]
	v_mfma_f32_16x16x32_bf16 v[72:75], v[214:217], v[186:189], v[72:75]
	v_mfma_f32_16x16x32_bf16 v[68:71], v[206:209], v[198:201], v[68:71]
	v_mfma_f32_16x16x32_bf16 v[64:67], v[214:217], v[198:201], v[64:67]
	s_setprio 0
	s_mov_b32 m0, s59
	v_lshl_add_u64 v[190:191], v[220:221], 0, s[14:15]
	s_barrier
	ds_read_b128 v[166:169], v149 offset:49152
	ds_read_b128 v[170:173], v149 offset:50176
	ds_read_b128 v[174:177], v149 offset:51200
	ds_read_b128 v[178:181], v149 offset:52224
	ds_read_b128 v[182:185], v149 offset:53248
	ds_read_b128 v[186:189], v149 offset:54272
	ds_read_b128 v[194:197], v149 offset:55296
	ds_read_b128 v[198:201], v149 offset:56320
	global_load_lds_dwordx4 v[190:191], off
	v_lshl_add_u64 v[190:191], v[222:223], 0, s[14:15]
	s_mov_b32 m0, s61
	s_nop 0
	global_load_lds_dwordx4 v[190:191], off
	s_barrier
; __device__ __forceinline__ unsigned cvt_pk_bf16(float lo, float hi) { unsigned r; asm volatile("v_cvt_pk_bf16_f32 %0, %1, %2" : "=v"(r) : "v"(lo), "v"(hi)); return r; }
; #define PG8_STAGE(bufoff, gbase, voff) do { _Pragma("unroll") for (int _i = 0; _i < 2; ++_i) \
;         __builtin_amdgcn_global_load_lds((const unsigned*)((const char*)(gbase) + (voff)[_i]), (LAS unsigned*)(lds + (bufoff) + ldsw + _i * 8192), 16, 0, 0); } while (0)
; #define PG8_MMA(ai, bj, At, Bt) do { __builtin_amdgcn_s_setprio(1); _Pragma("unroll") for (int m = 0; m < 4; ++m) _Pragma("unroll") for (int n = 0; n < 2; ++n) _Pragma("unroll") for (int k = 0; k < 2; ++k) \
;         acc[ai][bj][m][n] = __builtin_amdgcn_mfma_f32_16x16x32_bf16(Bt[n][k], At[m][k], acc[ai][bj][m][n], 0, 0, 0); __builtin_amdgcn_s_setprio(0); } while (0)
; #define PG8_WAIT_V(n) asm volatile("s_waitcnt vmcnt(" #n ")" ::: "memory")
; #define PG8_WAIT_L(n) asm volatile("s_waitcnt lgkmcnt(" #n ")" ::: "memory")
; #define PG8_BAR __builtin_amdgcn_s_barrier()
; #define PG8_SCHED __builtin_amdgcn_sched_barrier(0)
; template <class Epi>
; __device__ __forceinline__ void gemm_phase(LAS unsigned char* lds, const Gemm g, const Sched& S, const Epi& E) {
;     ...
;             PG8_BAR; PG8_WAIT_L(0); PG8_MMA(1, 0, At, B0); PG8_BAR; PG8_SCHED;
;             PG8_STAGE(PG8_SB(1, 1), b3 + hstepB, voffB);
;             PG8_WAIT_V(6); PG8_BAR; PG8_MMA(1, 1, At, B1); PG8_BAR;
;     __device__ __forceinline__ void operator()(AccRef acc, const Unit& u, int wr, int wc, int fr, int fq) const {
;     ...
;             for (int m = 0; m < 4; ++m) { const size_t row = (size_t)u.pm * 256 + ai * 128 + wr * 64 + m * 16 + fr; float o[8];
; #pragma unroll
;                 for (int bj = 0; bj < 2; ++bj) { const f32x4 gg = acc[ai][bj][m][0], uu = acc[ai][bj][m][1];
; #pragma unroll
;                     for (int j = 0; j < 4; ++j) o[4 * bj + j] = gg[j] * __builtin_amdgcn_rcpf(1.0f + __expf(-gg[j])) * uu[j]; }
;                 u32x4 w; w.x = cvt_pk_bf16(o[0], o[1]); w.y = cvt_pk_bf16(o[2], o[3]); w.z = cvt_pk_bf16(o[4], o[5]); w.w = cvt_pk_bf16(o[6], o[7]);
;                 *(u32x4*)(act + row * FF_ + (u.pn * 4 + wc) * 32 + 8 * fq) = w; }
	s_waitcnt lgkmcnt(0)
	s_setprio 1
	s_waitcnt lgkmcnt(0)
	v_mfma_f32_16x16x32_bf16 v[60:63], v[150:153], v[166:169], v[60:63]
	v_mfma_f32_16x16x32_bf16 v[56:59], v[158:161], v[166:169], v[56:59]
	v_mfma_f32_16x16x32_bf16 v[52:55], v[150:153], v[174:177], v[52:55]
	v_mfma_f32_16x16x32_bf16 v[48:51], v[158:161], v[174:177], v[48:51]
	v_mfma_f32_16x16x32_bf16 v[44:47], v[150:153], v[182:185], v[44:47]
	v_mfma_f32_16x16x32_bf16 v[40:43], v[158:161], v[182:185], v[40:43]
	v_mfma_f32_16x16x32_bf16 v[36:39], v[150:153], v[194:197], v[36:39]
	v_mfma_f32_16x16x32_bf16 v[32:35], v[158:161], v[194:197], v[32:35]
	v_mfma_f32_16x16x32_bf16 v[60:63], v[154:157], v[170:173], v[60:63]
	v_mfma_f32_16x16x32_bf16 v[56:59], v[162:165], v[170:173], v[56:59]
	v_mfma_f32_16x16x32_bf16 v[52:55], v[154:157], v[178:181], v[52:55]
	v_mfma_f32_16x16x32_bf16 v[48:51], v[162:165], v[178:181], v[48:51]
	v_mfma_f32_16x16x32_bf16 v[44:47], v[154:157], v[186:189], v[44:47]
	v_mfma_f32_16x16x32_bf16 v[40:43], v[162:165], v[186:189], v[40:43]
	v_mfma_f32_16x16x32_bf16 v[36:39], v[154:157], v[198:201], v[36:39]
	v_mfma_f32_16x16x32_bf16 v[32:35], v[162:165], v[198:201], v[32:35]
	s_setprio 0
	s_barrier
	s_add_u32 s38, s38, 0x80080
	s_addc_u32 s39, s39, 0
	s_add_i32 s52, s52, s1
	v_lshl_add_u64 v[150:151], s[38:39], 0, v[130:131]
	s_mov_b32 m0, s52
	s_nop 0
	global_load_lds_dwordx4 v[150:151], off
	v_lshl_add_u64 v[150:151], s[38:39], 0, v[128:129]
	s_add_i32 m0, s52, 0x2000
	s_nop 0
	global_load_lds_dwordx4 v[150:151], off
	s_waitcnt vmcnt(6)
	s_barrier
	s_setprio 1
	v_mfma_f32_16x16x32_bf16 v[28:31], v[202:205], v[166:169], v[28:31]
	v_mfma_f32_16x16x32_bf16 v[24:27], v[210:213], v[166:169], v[24:27]
	v_mfma_f32_16x16x32_bf16 v[20:23], v[202:205], v[174:177], v[20:23]
	v_mfma_f32_16x16x32_bf16 v[16:19], v[210:213], v[174:177], v[16:19]
	v_mfma_f32_16x16x32_bf16 v[12:15], v[202:205], v[182:185], v[12:15]
	v_mfma_f32_16x16x32_bf16 v[8:11], v[210:213], v[182:185], v[8:11]
	v_mfma_f32_16x16x32_bf16 v[4:7], v[202:205], v[194:197], v[4:7]
	v_mfma_f32_16x16x32_bf16 v[0:3], v[210:213], v[194:197], v[0:3]
	v_mfma_f32_16x16x32_bf16 v[28:31], v[206:209], v[170:173], v[28:31]
	v_mfma_f32_16x16x32_bf16 v[24:27], v[214:217], v[170:173], v[24:27]
	v_mfma_f32_16x16x32_bf16 v[20:23], v[206:209], v[178:181], v[20:23]
	v_mfma_f32_16x16x32_bf16 v[16:19], v[214:217], v[178:181], v[16:19]
	v_mfma_f32_16x16x32_bf16 v[12:15], v[206:209], v[186:189], v[12:15]
	v_mfma_f32_16x16x32_bf16 v[8:11], v[214:217], v[186:189], v[8:11]
	v_mfma_f32_16x16x32_bf16 v[4:7], v[206:209], v[198:201], v[4:7]
	v_mfma_f32_16x16x32_bf16 v[0:3], v[214:217], v[198:201], v[0:3]
	s_setprio 0
	s_add_i32 s70, s70, 2
	s_add_u32 s24, s24, 0x100
	s_addc_u32 s25, s25, 0
	s_cmp_gt_u32 s70, 29
	s_barrier
	s_cbranch_scc0 .LBB0_177
	v_mov_b32_e32 v170, 0xbfb8aa3b
	v_mov_b32_e32 v172, 1.0
	v_mov_b64_e32 v[176:177], 0
	v_mov_b64_e32 v[178:179], 0
	s_add_u32 s24, s9, 0xffffff00
	s_addc_u32 s25, s51, -1
	s_ashr_i32 s9, s8, 31
	s_lshl_b64 s[38:39], s[8:9], 8
	v_lshl_add_u64 v[144:145], v[134:135], 0, s[38:39]
	v_mov_b64_e32 v[146:147], s[44:45]
	v_mad_u64_u32 v[146:147], s[52:53], v144, s64, v[146:147]
	s_lshl_b32 s9, s57, 7
	v_mov_b32_e32 v144, v147
	s_or_b32 s38, s9, s58
	v_mad_u64_u32 v[144:145], s[52:53], v145, s64, v[144:145]
	s_ashr_i32 s39, s38, 31
	v_mov_b32_e32 v147, v144
	v_lshl_add_u64 v[144:145], s[38:39], 1, v[146:147]
	v_lshl_add_u64 v[144:145], v[144:145], 0, v[132:133]
	v_pk_mul_f32 v[162:163], v[124:125], v[170:171] op_sel_hi:[1,0]
	v_pk_mul_f32 v[164:165], v[126:127], v[170:171] op_sel_hi:[1,0]
	v_pk_mul_f32 v[166:167], v[92:93], v[170:171] op_sel_hi:[1,0]
	v_pk_mul_f32 v[168:169], v[94:95], v[170:171] op_sel_hi:[1,0]
	v_exp_f32_e32 v162, v162
	v_exp_f32_e32 v163, v163
	v_exp_f32_e32 v164, v164
	v_exp_f32_e32 v165, v165
	v_exp_f32_e32 v166, v166
	v_exp_f32_e32 v167, v167
	v_exp_f32_e32 v168, v168
	v_exp_f32_e32 v169, v169
	v_pk_add_f32 v[162:163], v[162:163], v[172:173] op_sel_hi:[1,0]
	v_pk_add_f32 v[164:165], v[164:165], v[172:173] op_sel_hi:[1,0]
	v_pk_add_f32 v[166:167], v[166:167], v[172:173] op_sel_hi:[1,0]
	v_pk_add_f32 v[168:169], v[168:169], v[172:173] op_sel_hi:[1,0]
	v_rcp_f32_e32 v162, v162
	v_rcp_f32_e32 v163, v163
	v_rcp_f32_e32 v164, v164
	v_rcp_f32_e32 v165, v165
	v_rcp_f32_e32 v166, v166
	v_rcp_f32_e32 v167, v167
	v_rcp_f32_e32 v168, v168
	v_rcp_f32_e32 v169, v169
	v_pk_mul_f32 v[162:163], v[124:125], v[162:163]
	v_pk_mul_f32 v[164:165], v[126:127], v[164:165]
	v_pk_mul_f32 v[166:167], v[92:93], v[166:167]
	v_pk_mul_f32 v[168:169], v[94:95], v[168:169]
	v_pk_mul_f32 v[162:163], v[120:121], v[162:163]
	v_pk_mul_f32 v[164:165], v[122:123], v[164:165]
	v_pk_mul_f32 v[166:167], v[88:89], v[166:167]
	v_pk_mul_f32 v[168:169], v[90:91], v[168:169]
	v_cvt_pk_bf16_f32 v150, v162, v163
	v_cvt_pk_bf16_f32 v151, v164, v165
	v_cvt_pk_bf16_f32 v152, v166, v167
	v_cvt_pk_bf16_f32 v153, v168, v169
	global_store_dwordx4 v[144:145], v[150:153], off nt
	s_mov_b32 s9, 0x2c000
	v_add_co_u32_e32 v146, vcc, s9, v144
	s_nop 0
	v_addc_co_u32_e32 v147, vcc, 0, v145, vcc
	v_pk_mul_f32 v[162:163], v[116:117], v[170:171] op_sel_hi:[1,0]
	v_pk_mul_f32 v[164:165], v[118:119], v[170:171] op_sel_hi:[1,0]
	v_pk_mul_f32 v[166:167], v[84:85], v[170:171] op_sel_hi:[1,0]
	v_pk_mul_f32 v[168:169], v[86:87], v[170:171] op_sel_hi:[1,0]
	v_exp_f32_e32 v162, v162
	v_exp_f32_e32 v163, v163
	v_exp_f32_e32 v164, v164
	v_exp_f32_e32 v165, v165
	v_exp_f32_e32 v166, v166
	v_exp_f32_e32 v167, v167
	v_exp_f32_e32 v168, v168
	v_exp_f32_e32 v169, v169
	v_pk_add_f32 v[162:163], v[162:163], v[172:173] op_sel_hi:[1,0]
	v_pk_add_f32 v[164:165], v[164:165], v[172:173] op_sel_hi:[1,0]
; __device__ __forceinline__ unsigned cvt_pk_bf16(float lo, float hi) { unsigned r; asm volatile("v_cvt_pk_bf16_f32 %0, %1, %2" : "=v"(r) : "v"(lo), "v"(hi)); return r; }
;     __device__ __forceinline__ void operator()(AccRef acc, const Unit& u, int wr, int wc, int fr, int fq) const {
;     ...
;             for (int m = 0; m < 4; ++m) { const size_t row = (size_t)u.pm * 256 + ai * 128 + wr * 64 + m * 16 + fr; float o[8];
; #pragma unroll
;                 for (int bj = 0; bj < 2; ++bj) { const f32x4 gg = acc[ai][bj][m][0], uu = acc[ai][bj][m][1];
; #pragma unroll
;                     for (int j = 0; j < 4; ++j) o[4 * bj + j] = gg[j] * __builtin_amdgcn_rcpf(1.0f + __expf(-gg[j])) * uu[j]; }
;                 u32x4 w; w.x = cvt_pk_bf16(o[0], o[1]); w.y = cvt_pk_bf16(o[2], o[3]); w.z = cvt_pk_bf16(o[4], o[5]); w.w = cvt_pk_bf16(o[6], o[7]);
;                 *(u32x4*)(act + row * FF_ + (u.pn * 4 + wc) * 32 + 8 * fq) = w; }
	v_pk_add_f32 v[166:167], v[166:167], v[172:173] op_sel_hi:[1,0]
	v_pk_add_f32 v[168:169], v[168:169], v[172:173] op_sel_hi:[1,0]
	v_rcp_f32_e32 v162, v162
	v_rcp_f32_e32 v163, v163
	v_rcp_f32_e32 v164, v164
	v_rcp_f32_e32 v165, v165
	v_rcp_f32_e32 v166, v166
	v_rcp_f32_e32 v167, v167
	v_rcp_f32_e32 v168, v168
	v_rcp_f32_e32 v169, v169
	v_pk_mul_f32 v[162:163], v[116:117], v[162:163]
	v_pk_mul_f32 v[164:165], v[118:119], v[164:165]
	v_pk_mul_f32 v[166:167], v[84:85], v[166:167]
	v_pk_mul_f32 v[168:169], v[86:87], v[168:169]
	v_pk_mul_f32 v[162:163], v[112:113], v[162:163]
	v_pk_mul_f32 v[164:165], v[114:115], v[164:165]
	v_pk_mul_f32 v[166:167], v[80:81], v[166:167]
	v_pk_mul_f32 v[168:169], v[82:83], v[168:169]
	v_cvt_pk_bf16_f32 v150, v162, v163
	v_cvt_pk_bf16_f32 v151, v164, v165
	v_cvt_pk_bf16_f32 v152, v166, v167
	v_cvt_pk_bf16_f32 v153, v168, v169
	global_store_dwordx4 v[146:147], v[150:153], off nt
	v_mfma_f32_32x32x16_bf16 v[80:95], v[176:179], v[176:179], 0
	v_mfma_f32_32x32x16_bf16 v[112:127], v[176:179], v[176:179], 0
	s_mov_b32 s9, 0x58000
	v_add_co_u32_e32 v146, vcc, s9, v144
	s_nop 0
	v_addc_co_u32_e32 v147, vcc, 0, v145, vcc
	v_pk_mul_f32 v[162:163], v[108:109], v[170:171] op_sel_hi:[1,0]
	v_pk_mul_f32 v[164:165], v[110:111], v[170:171] op_sel_hi:[1,0]
	v_pk_mul_f32 v[166:167], v[76:77], v[170:171] op_sel_hi:[1,0]
	v_pk_mul_f32 v[168:169], v[78:79], v[170:171] op_sel_hi:[1,0]
	v_exp_f32_e32 v162, v162
	v_exp_f32_e32 v163, v163
	v_exp_f32_e32 v164, v164
	v_exp_f32_e32 v165, v165
	v_exp_f32_e32 v166, v166
	v_exp_f32_e32 v167, v167
	v_exp_f32_e32 v168, v168
	v_exp_f32_e32 v169, v169
	v_pk_add_f32 v[162:163], v[162:163], v[172:173] op_sel_hi:[1,0]
	v_pk_add_f32 v[164:165], v[164:165], v[172:173] op_sel_hi:[1,0]
	v_pk_add_f32 v[166:167], v[166:167], v[172:173] op_sel_hi:[1,0]
	v_pk_add_f32 v[168:169], v[168:169], v[172:173] op_sel_hi:[1,0]
	v_rcp_f32_e32 v162, v162
	v_rcp_f32_e32 v163, v163
	v_rcp_f32_e32 v164, v164
	v_rcp_f32_e32 v165, v165
	v_rcp_f32_e32 v166, v166
	v_rcp_f32_e32 v167, v167
	v_rcp_f32_e32 v168, v168
	v_rcp_f32_e32 v169, v169
	v_pk_mul_f32 v[162:163], v[108:109], v[162:163]
	v_pk_mul_f32 v[164:165], v[110:111], v[164:165]
	v_pk_mul_f32 v[166:167], v[76:77], v[166:167]
	v_pk_mul_f32 v[168:169], v[78:79], v[168:169]
	v_pk_mul_f32 v[162:163], v[104:105], v[162:163]
	v_pk_mul_f32 v[164:165], v[106:107], v[164:165]
	v_pk_mul_f32 v[166:167], v[72:73], v[166:167]
	v_pk_mul_f32 v[168:169], v[74:75], v[168:169]
	v_cvt_pk_bf16_f32 v150, v162, v163
	v_cvt_pk_bf16_f32 v151, v164, v165
	v_cvt_pk_bf16_f32 v152, v166, v167
	v_cvt_pk_bf16_f32 v153, v168, v169
	global_store_dwordx4 v[146:147], v[150:153], off nt
	s_mov_b32 s9, 0x84000
	v_add_co_u32_e32 v146, vcc, s9, v144
	s_nop 0
	v_addc_co_u32_e32 v147, vcc, 0, v145, vcc
	v_pk_mul_f32 v[162:163], v[100:101], v[170:171] op_sel_hi:[1,0]
	v_pk_mul_f32 v[164:165], v[102:103], v[170:171] op_sel_hi:[1,0]
	v_pk_mul_f32 v[166:167], v[68:69], v[170:171] op_sel_hi:[1,0]
	v_pk_mul_f32 v[168:169], v[70:71], v[170:171] op_sel_hi:[1,0]
	v_exp_f32_e32 v162, v162
	v_exp_f32_e32 v163, v163
	v_exp_f32_e32 v164, v164
	v_exp_f32_e32 v165, v165
	v_exp_f32_e32 v166, v166
	v_exp_f32_e32 v167, v167
	v_exp_f32_e32 v168, v168
	v_exp_f32_e32 v169, v169
	v_pk_add_f32 v[162:163], v[162:163], v[172:173] op_sel_hi:[1,0]
	v_pk_add_f32 v[164:165], v[164:165], v[172:173] op_sel_hi:[1,0]
	v_pk_add_f32 v[166:167], v[166:167], v[172:173] op_sel_hi:[1,0]
	v_pk_add_f32 v[168:169], v[168:169], v[172:173] op_sel_hi:[1,0]
	v_rcp_f32_e32 v162, v162
	v_rcp_f32_e32 v163, v163
	v_rcp_f32_e32 v164, v164
	v_rcp_f32_e32 v165, v165
	v_rcp_f32_e32 v166, v166
	v_rcp_f32_e32 v167, v167
	v_rcp_f32_e32 v168, v168
	v_rcp_f32_e32 v169, v169
	v_pk_mul_f32 v[162:163], v[100:101], v[162:163]
	v_pk_mul_f32 v[164:165], v[102:103], v[164:165]
	v_pk_mul_f32 v[166:167], v[68:69], v[166:167]
	v_pk_mul_f32 v[168:169], v[70:71], v[168:169]
	v_pk_mul_f32 v[162:163], v[96:97], v[162:163]
	v_pk_mul_f32 v[164:165], v[98:99], v[164:165]
	v_pk_mul_f32 v[166:167], v[64:65], v[166:167]
	v_pk_mul_f32 v[168:169], v[66:67], v[168:169]
	v_cvt_pk_bf16_f32 v150, v162, v163
	v_cvt_pk_bf16_f32 v151, v164, v165
	v_cvt_pk_bf16_f32 v152, v166, v167
	v_cvt_pk_bf16_f32 v153, v168, v169
	global_store_dwordx4 v[146:147], v[150:153], off nt
	v_mfma_f32_32x32x16_bf16 v[64:79], v[176:179], v[176:179], 0
	v_mfma_f32_32x32x16_bf16 v[96:111], v[176:179], v[176:179], 0
	s_mov_b32 s9, 0x160000
	v_add_co_u32_e32 v146, vcc, s9, v144
	s_nop 0
	v_addc_co_u32_e32 v147, vcc, 0, v145, vcc
	v_pk_mul_f32 v[162:163], v[60:61], v[170:171] op_sel_hi:[1,0]
	v_pk_mul_f32 v[164:165], v[62:63], v[170:171] op_sel_hi:[1,0]
	v_pk_mul_f32 v[166:167], v[28:29], v[170:171] op_sel_hi:[1,0]
	v_pk_mul_f32 v[168:169], v[30:31], v[170:171] op_sel_hi:[1,0]
	v_exp_f32_e32 v162, v162
	v_exp_f32_e32 v163, v163
	v_exp_f32_e32 v164, v164
	v_exp_f32_e32 v165, v165
	v_exp_f32_e32 v166, v166
	v_exp_f32_e32 v167, v167
	v_exp_f32_e32 v168, v168
	v_exp_f32_e32 v169, v169
	v_pk_add_f32 v[162:163], v[162:163], v[172:173] op_sel_hi:[1,0]
	v_pk_add_f32 v[164:165], v[164:165], v[172:173] op_sel_hi:[1,0]
	v_pk_add_f32 v[166:167], v[166:167], v[172:173] op_sel_hi:[1,0]
	v_pk_add_f32 v[168:169], v[168:169], v[172:173] op_sel_hi:[1,0]
	v_rcp_f32_e32 v162, v162
	v_rcp_f32_e32 v163, v163
	v_rcp_f32_e32 v164, v164
	v_rcp_f32_e32 v165, v165
	v_rcp_f32_e32 v166, v166
	v_rcp_f32_e32 v167, v167
	v_rcp_f32_e32 v168, v168
	v_rcp_f32_e32 v169, v169
	v_pk_mul_f32 v[162:163], v[60:61], v[162:163]
	v_pk_mul_f32 v[164:165], v[62:63], v[164:165]
	v_pk_mul_f32 v[166:167], v[28:29], v[166:167]
; __device__ __forceinline__ unsigned cvt_pk_bf16(float lo, float hi) { unsigned r; asm volatile("v_cvt_pk_bf16_f32 %0, %1, %2" : "=v"(r) : "v"(lo), "v"(hi)); return r; }
; template <class Epi>
; __device__ __forceinline__ void gemm_phase(LAS unsigned char* lds, const Gemm g, const Sched& S, const Epi& E) {
;     ...
;         if (!has_next) break;
; #pragma unroll
;         for (int a = 0; a < 2; ++a)
; #pragma unroll
;             for (int b = 0; b < 2; ++b)
; #pragma unroll
;                 for (int m = 0; m < 4; ++m)
; #pragma unroll
;                     for (int n = 0; n < 2; ++n) acc[a][b][m][n] = (f32x4){0.f, 0.f, 0.f, 0.f};
;         cur = nxt; cA = nA; cB = nB; ++ui;
;     __device__ __forceinline__ void operator()(AccRef acc, const Unit& u, int wr, int wc, int fr, int fq) const {
;     ...
;             for (int m = 0; m < 4; ++m) { const size_t row = (size_t)u.pm * 256 + ai * 128 + wr * 64 + m * 16 + fr; float o[8];
; #pragma unroll
;                 for (int bj = 0; bj < 2; ++bj) { const f32x4 gg = acc[ai][bj][m][0], uu = acc[ai][bj][m][1];
; #pragma unroll
;                     for (int j = 0; j < 4; ++j) o[4 * bj + j] = gg[j] * __builtin_amdgcn_rcpf(1.0f + __expf(-gg[j])) * uu[j]; }
;                 u32x4 w; w.x = cvt_pk_bf16(o[0], o[1]); w.y = cvt_pk_bf16(o[2], o[3]); w.z = cvt_pk_bf16(o[4], o[5]); w.w = cvt_pk_bf16(o[6], o[7]);
;                 *(u32x4*)(act + row * FF_ + (u.pn * 4 + wc) * 32 + 8 * fq) = w; }
	v_pk_mul_f32 v[168:169], v[30:31], v[168:169]
	v_pk_mul_f32 v[162:163], v[56:57], v[162:163]
	v_pk_mul_f32 v[164:165], v[58:59], v[164:165]
	v_pk_mul_f32 v[166:167], v[24:25], v[166:167]
	v_pk_mul_f32 v[168:169], v[26:27], v[168:169]
	v_cvt_pk_bf16_f32 v150, v162, v163
	v_cvt_pk_bf16_f32 v151, v164, v165
	v_cvt_pk_bf16_f32 v152, v166, v167
	v_cvt_pk_bf16_f32 v153, v168, v169
	global_store_dwordx4 v[146:147], v[150:153], off nt
	s_mov_b32 s9, 0x18c000
	v_add_co_u32_e32 v146, vcc, s9, v144
	s_nop 0
	v_addc_co_u32_e32 v147, vcc, 0, v145, vcc
	v_pk_mul_f32 v[162:163], v[52:53], v[170:171] op_sel_hi:[1,0]
	v_pk_mul_f32 v[164:165], v[54:55], v[170:171] op_sel_hi:[1,0]
	v_pk_mul_f32 v[166:167], v[20:21], v[170:171] op_sel_hi:[1,0]
	v_pk_mul_f32 v[168:169], v[22:23], v[170:171] op_sel_hi:[1,0]
	v_exp_f32_e32 v162, v162
	v_exp_f32_e32 v163, v163
	v_exp_f32_e32 v164, v164
	v_exp_f32_e32 v165, v165
	v_exp_f32_e32 v166, v166
	v_exp_f32_e32 v167, v167
	v_exp_f32_e32 v168, v168
	v_exp_f32_e32 v169, v169
	v_pk_add_f32 v[162:163], v[162:163], v[172:173] op_sel_hi:[1,0]
	v_pk_add_f32 v[164:165], v[164:165], v[172:173] op_sel_hi:[1,0]
	v_pk_add_f32 v[166:167], v[166:167], v[172:173] op_sel_hi:[1,0]
	v_pk_add_f32 v[168:169], v[168:169], v[172:173] op_sel_hi:[1,0]
	v_rcp_f32_e32 v162, v162
	v_rcp_f32_e32 v163, v163
	v_rcp_f32_e32 v164, v164
	v_rcp_f32_e32 v165, v165
	v_rcp_f32_e32 v166, v166
	v_rcp_f32_e32 v167, v167
	v_rcp_f32_e32 v168, v168
	v_rcp_f32_e32 v169, v169
	v_pk_mul_f32 v[162:163], v[52:53], v[162:163]
	v_pk_mul_f32 v[164:165], v[54:55], v[164:165]
	v_pk_mul_f32 v[166:167], v[20:21], v[166:167]
	v_pk_mul_f32 v[168:169], v[22:23], v[168:169]
	v_pk_mul_f32 v[162:163], v[48:49], v[162:163]
	v_pk_mul_f32 v[164:165], v[50:51], v[164:165]
	v_pk_mul_f32 v[166:167], v[16:17], v[166:167]
	v_pk_mul_f32 v[168:169], v[18:19], v[168:169]
	v_cvt_pk_bf16_f32 v150, v162, v163
	v_cvt_pk_bf16_f32 v151, v164, v165
	v_cvt_pk_bf16_f32 v152, v166, v167
	v_cvt_pk_bf16_f32 v153, v168, v169
	global_store_dwordx4 v[146:147], v[150:153], off nt
	v_mfma_f32_32x32x16_bf16 v[16:31], v[176:179], v[176:179], 0
	v_mfma_f32_32x32x16_bf16 v[48:63], v[176:179], v[176:179], 0
	v_add_co_u32_e32 v146, vcc, s65, v144
	s_nop 0
	v_addc_co_u32_e32 v147, vcc, 0, v145, vcc
	v_pk_mul_f32 v[162:163], v[44:45], v[170:171] op_sel_hi:[1,0]
	v_pk_mul_f32 v[164:165], v[46:47], v[170:171] op_sel_hi:[1,0]
	v_pk_mul_f32 v[166:167], v[12:13], v[170:171] op_sel_hi:[1,0]
	v_pk_mul_f32 v[168:169], v[14:15], v[170:171] op_sel_hi:[1,0]
	v_exp_f32_e32 v162, v162
	v_exp_f32_e32 v163, v163
	v_exp_f32_e32 v164, v164
	v_exp_f32_e32 v165, v165
	v_exp_f32_e32 v166, v166
	v_exp_f32_e32 v167, v167
	v_exp_f32_e32 v168, v168
	v_exp_f32_e32 v169, v169
	v_pk_add_f32 v[162:163], v[162:163], v[172:173] op_sel_hi:[1,0]
	v_pk_add_f32 v[164:165], v[164:165], v[172:173] op_sel_hi:[1,0]
	v_pk_add_f32 v[166:167], v[166:167], v[172:173] op_sel_hi:[1,0]
	v_pk_add_f32 v[168:169], v[168:169], v[172:173] op_sel_hi:[1,0]
	v_rcp_f32_e32 v162, v162
	v_rcp_f32_e32 v163, v163
	v_rcp_f32_e32 v164, v164
	v_rcp_f32_e32 v165, v165
	v_rcp_f32_e32 v166, v166
	v_rcp_f32_e32 v167, v167
	v_rcp_f32_e32 v168, v168
	v_rcp_f32_e32 v169, v169
	v_pk_mul_f32 v[162:163], v[44:45], v[162:163]
	v_pk_mul_f32 v[164:165], v[46:47], v[164:165]
	v_pk_mul_f32 v[166:167], v[12:13], v[166:167]
	v_pk_mul_f32 v[168:169], v[14:15], v[168:169]
	v_pk_mul_f32 v[162:163], v[40:41], v[162:163]
	v_pk_mul_f32 v[164:165], v[42:43], v[164:165]
	v_pk_mul_f32 v[166:167], v[8:9], v[166:167]
	v_pk_mul_f32 v[168:169], v[10:11], v[168:169]
	v_cvt_pk_bf16_f32 v150, v162, v163
	v_cvt_pk_bf16_f32 v151, v164, v165
	v_cvt_pk_bf16_f32 v152, v166, v167
	v_cvt_pk_bf16_f32 v153, v168, v169
	global_store_dwordx4 v[146:147], v[150:153], off nt
	v_add_co_u32_e32 v144, vcc, 0x1e4000, v144
	v_addc_co_u32_e32 v145, vcc, 0, v145, vcc
	s_andn2_b64 vcc, exec, s[6:7]
	v_pk_mul_f32 v[162:163], v[36:37], v[170:171] op_sel_hi:[1,0]
	v_pk_mul_f32 v[164:165], v[38:39], v[170:171] op_sel_hi:[1,0]
	v_pk_mul_f32 v[166:167], v[4:5], v[170:171] op_sel_hi:[1,0]
	v_pk_mul_f32 v[168:169], v[6:7], v[170:171] op_sel_hi:[1,0]
	v_exp_f32_e32 v162, v162
	v_exp_f32_e32 v163, v163
	v_exp_f32_e32 v164, v164
	v_exp_f32_e32 v165, v165
	v_exp_f32_e32 v166, v166
	v_exp_f32_e32 v167, v167
	v_exp_f32_e32 v168, v168
	v_exp_f32_e32 v169, v169
	v_pk_add_f32 v[162:163], v[162:163], v[172:173] op_sel_hi:[1,0]
	v_pk_add_f32 v[164:165], v[164:165], v[172:173] op_sel_hi:[1,0]
	v_pk_add_f32 v[166:167], v[166:167], v[172:173] op_sel_hi:[1,0]
	v_pk_add_f32 v[168:169], v[168:169], v[172:173] op_sel_hi:[1,0]
	v_rcp_f32_e32 v162, v162
	v_rcp_f32_e32 v163, v163
	v_rcp_f32_e32 v164, v164
	v_rcp_f32_e32 v165, v165
	v_rcp_f32_e32 v166, v166
	v_rcp_f32_e32 v167, v167
	v_rcp_f32_e32 v168, v168
	v_rcp_f32_e32 v169, v169
	v_pk_mul_f32 v[162:163], v[36:37], v[162:163]
	v_pk_mul_f32 v[164:165], v[38:39], v[164:165]
	v_pk_mul_f32 v[166:167], v[4:5], v[166:167]
	v_pk_mul_f32 v[168:169], v[6:7], v[168:169]
	v_pk_mul_f32 v[162:163], v[32:33], v[162:163]
	v_pk_mul_f32 v[164:165], v[34:35], v[164:165]
	v_pk_mul_f32 v[166:167], v[0:1], v[166:167]
	v_pk_mul_f32 v[168:169], v[2:3], v[168:169]
	v_cvt_pk_bf16_f32 v150, v162, v163
	v_cvt_pk_bf16_f32 v151, v164, v165
	v_cvt_pk_bf16_f32 v152, v166, v167
	v_cvt_pk_bf16_f32 v153, v168, v169
	global_store_dwordx4 v[144:145], v[150:153], off nt
	v_mfma_f32_32x32x16_bf16 v[0:15], v[176:179], v[176:179], 0
	v_mfma_f32_32x32x16_bf16 v[32:47], v[176:179], v[176:179], 0
	s_cbranch_vccz .LBB0_173
	s_mov_b64 s[20:21], s[24:25]
	s_andn2_b64 vcc, exec, s[4:5]
	s_mov_b64 s[24:25], s[20:21]
	s_cbranch_vccnz .LBB0_174

; #define PG8_STAGE(bufoff, gbase, voff) do { _Pragma("unroll") for (int _i = 0; _i < 2; ++_i) \
;         __builtin_amdgcn_global_load_lds((const unsigned*)((const char*)(gbase) + (voff)[_i]), (LAS unsigned*)(lds + (bufoff) + ldsw + _i * 8192), 16, 0, 0); } while (0)
; #define PG8_LDA(dst, b, h) do { _Pragma("unroll") for (int m = 0; m < 4; ++m) _Pragma("unroll") for (int k = 0; k < 2; ++k) dst[m][k] = *(const LAS bf16x8*)(lds + PG8_SA(b, h) + aoff + m * 2048 + k * 1024); } while (0)
; #define PG8_LDB(dst, b, h) do { _Pragma("unroll") for (int n = 0; n < 2; ++n) _Pragma("unroll") for (int k = 0; k < 2; ++k) dst[n][k] = *(const LAS bf16x8*)(lds + PG8_SB(b, h) + boff + n * 2048 + k * 1024); } while (0)
; #define PG8_MMA(ai, bj, At, Bt) do { __builtin_amdgcn_s_setprio(1); _Pragma("unroll") for (int m = 0; m < 4; ++m) _Pragma("unroll") for (int n = 0; n < 2; ++n) _Pragma("unroll") for (int k = 0; k < 2; ++k) \
;         acc[ai][bj][m][n] = __builtin_amdgcn_mfma_f32_16x16x32_bf16(Bt[n][k], At[m][k], acc[ai][bj][m][n], 0, 0, 0); __builtin_amdgcn_s_setprio(0); } while (0)
; #define PG8_WAIT_L(n) asm volatile("s_waitcnt lgkmcnt(" #n ")" ::: "memory")
; #define PG8_BAR __builtin_amdgcn_s_barrier()
; #define PG8_SCHED __builtin_amdgcn_sched_barrier(0)
; template <class Epi>
; __device__ __forceinline__ void gemm_phase(LAS unsigned char* lds, const Gemm g, const Sched& S, const Epi& E) {
;     ...
;             PG8_LDB(B0, 0, 0); PG8_SCHED; PG8_LDA(At, 0, 0); PG8_STAGE(PG8_SA(1, 1), a1 + hstepA, voffA);
;             PG8_WAIT_L(8); PG8_BAR; PG8_WAIT_L(0); PG8_MMA(0, 0, At, B0); PG8_BAR; PG8_SCHED;
;             PG8_LDB(B1, 0, 1); PG8_STAGE(PG8_SB(0, 0), b2, voffB);
;             PG8_BAR; PG8_WAIT_L(0); PG8_MMA(0, 1, At, B1); PG8_BAR;
;             PG8_LDA(At, 0, 1); PG8_STAGE(PG8_SA(0, 0), a2, voffA);
;             PG8_BAR; PG8_WAIT_L(0); PG8_MMA(1, 0, At, B0); PG8_BAR; PG8_SCHED;
.LBB0_2088:
	v_add_u32_e32 v162, s62, v148
	s_add_u32 s38, s14, s36
	ds_read_b128 v[150:153], v162
	ds_read_b128 v[154:157], v162 offset:1024
	ds_read_b128 v[158:161], v162 offset:2048
	ds_read_b128 v[162:165], v162 offset:3072
	s_addc_u32 s39, s15, s37
	s_add_u32 s38, s38, 0x100
	s_addc_u32 s39, s39, 0
	s_add_u32 s82, s13, s36
	s_addc_u32 s83, s51, s37
	s_cmpk_eq_i32 s36, 0xf00
	s_cselect_b32 s55, s21, s39
	s_cselect_b32 s54, s79, s38
	s_cselect_b32 s39, s19, s83
	s_cselect_b32 s38, s80, s82
	v_lshl_add_u64 v[190:191], v[144:145], 0, s[36:37]
	s_add_i32 m0, s43, 0xc000
	ds_read_b128 v[166:169], v149
	ds_read_b128 v[170:173], v149 offset:1024
	ds_read_b128 v[174:177], v149 offset:2048
	ds_read_b128 v[178:181], v149 offset:3072
	ds_read_b128 v[182:185], v149 offset:4096
	ds_read_b128 v[186:189], v149 offset:5120
	ds_read_b128 v[194:197], v149 offset:6144
	ds_read_b128 v[198:201], v149 offset:7168
	global_load_lds_dwordx4 v[190:191], off
	v_lshl_add_u64 v[190:191], v[146:147], 0, s[36:37]
	s_add_i32 m0, s43, 0xe000
	s_nop 0
	global_load_lds_dwordx4 v[190:191], off
	s_waitcnt lgkmcnt(8)
	s_barrier
	s_waitcnt lgkmcnt(0)
	s_setprio 1
	s_waitcnt lgkmcnt(0)
	v_mfma_f32_16x16x32_bf16 v[124:127], v[150:153], v[166:169], v[124:127]
	v_mfma_f32_16x16x32_bf16 v[120:123], v[158:161], v[166:169], v[120:123]
	v_mfma_f32_16x16x32_bf16 v[116:119], v[150:153], v[174:177], v[116:119]
	v_mfma_f32_16x16x32_bf16 v[112:115], v[158:161], v[174:177], v[112:115]
	v_mfma_f32_16x16x32_bf16 v[108:111], v[150:153], v[182:185], v[108:111]
	v_mfma_f32_16x16x32_bf16 v[104:107], v[158:161], v[182:185], v[104:107]
	v_mfma_f32_16x16x32_bf16 v[100:103], v[150:153], v[194:197], v[100:103]
	v_mfma_f32_16x16x32_bf16 v[96:99], v[158:161], v[194:197], v[96:99]
	v_mfma_f32_16x16x32_bf16 v[124:127], v[154:157], v[170:173], v[124:127]
	v_mfma_f32_16x16x32_bf16 v[120:123], v[162:165], v[170:173], v[120:123]
	v_mfma_f32_16x16x32_bf16 v[116:119], v[154:157], v[178:181], v[116:119]
	v_mfma_f32_16x16x32_bf16 v[112:115], v[162:165], v[178:181], v[112:115]
	v_mfma_f32_16x16x32_bf16 v[108:111], v[154:157], v[186:189], v[108:111]
	v_mfma_f32_16x16x32_bf16 v[104:107], v[162:165], v[186:189], v[104:107]
	v_mfma_f32_16x16x32_bf16 v[100:103], v[154:157], v[198:201], v[100:103]
	v_mfma_f32_16x16x32_bf16 v[96:99], v[162:165], v[198:201], v[96:99]
	s_setprio 0
	s_barrier
	v_add_u32_e32 v190, s63, v148
	s_add_i32 s82, s62, s34
	ds_read_b128 v[202:205], v190
	ds_read_b128 v[206:209], v190 offset:1024
	ds_read_b128 v[210:213], v190 offset:2048
	ds_read_b128 v[214:217], v190 offset:3072
	v_lshl_add_u64 v[190:191], s[38:39], 0, v[130:131]
	s_mov_b32 m0, s82
	v_lshl_add_u64 v[218:219], s[38:39], 0, v[128:129]
	global_load_lds_dwordx4 v[190:191], off
	s_add_i32 m0, s82, 0x2000
	s_nop 0
	global_load_lds_dwordx4 v[218:219], off
	s_barrier
	s_waitcnt lgkmcnt(0)
	s_setprio 1
	s_waitcnt lgkmcnt(0)
	v_mfma_f32_16x16x32_bf16 v[92:95], v[202:205], v[166:169], v[92:95]
	v_mfma_f32_16x16x32_bf16 v[88:91], v[210:213], v[166:169], v[88:91]
	v_mfma_f32_16x16x32_bf16 v[84:87], v[202:205], v[174:177], v[84:87]
	v_mfma_f32_16x16x32_bf16 v[80:83], v[210:213], v[174:177], v[80:83]
	v_mfma_f32_16x16x32_bf16 v[76:79], v[202:205], v[182:185], v[76:79]
	v_mfma_f32_16x16x32_bf16 v[72:75], v[210:213], v[182:185], v[72:75]
	v_mfma_f32_16x16x32_bf16 v[68:71], v[202:205], v[194:197], v[68:71]
	v_mfma_f32_16x16x32_bf16 v[64:67], v[210:213], v[194:197], v[64:67]
	v_mfma_f32_16x16x32_bf16 v[92:95], v[206:209], v[170:173], v[92:95]
	v_mfma_f32_16x16x32_bf16 v[88:91], v[214:217], v[170:173], v[88:91]
	v_mfma_f32_16x16x32_bf16 v[84:87], v[206:209], v[178:181], v[84:87]
	v_mfma_f32_16x16x32_bf16 v[80:83], v[214:217], v[178:181], v[80:83]
	v_mfma_f32_16x16x32_bf16 v[76:79], v[206:209], v[186:189], v[76:79]
	v_mfma_f32_16x16x32_bf16 v[72:75], v[214:217], v[186:189], v[72:75]
	v_mfma_f32_16x16x32_bf16 v[68:71], v[206:209], v[198:201], v[68:71]
	v_mfma_f32_16x16x32_bf16 v[64:67], v[214:217], v[198:201], v[64:67]
	s_setprio 0
	s_mov_b32 m0, s43
	v_lshl_add_u64 v[220:221], s[54:55], 0, v[130:131]
	s_barrier
	ds_read_b128 v[166:169], v149 offset:16384
	ds_read_b128 v[170:173], v149 offset:17408
	ds_read_b128 v[174:177], v149 offset:18432
	ds_read_b128 v[178:181], v149 offset:19456
	ds_read_b128 v[182:185], v149 offset:20480
	ds_read_b128 v[186:189], v149 offset:21504
	ds_read_b128 v[194:197], v149 offset:22528
	ds_read_b128 v[198:201], v149 offset:23552
	global_load_lds_dwordx4 v[220:221], off
	v_lshl_add_u64 v[222:223], s[54:55], 0, v[128:129]
	s_mov_b32 m0, s52
	s_nop 0
	global_load_lds_dwordx4 v[222:223], off
	s_barrier
	s_waitcnt lgkmcnt(0)
	s_setprio 1
	s_waitcnt lgkmcnt(0)
	v_mfma_f32_16x16x32_bf16 v[60:63], v[150:153], v[166:169], v[60:63]
	v_mfma_f32_16x16x32_bf16 v[56:59], v[158:161], v[166:169], v[56:59]
	v_mfma_f32_16x16x32_bf16 v[52:55], v[150:153], v[174:177], v[52:55]
	v_mfma_f32_16x16x32_bf16 v[48:51], v[158:161], v[174:177], v[48:51]
	v_mfma_f32_16x16x32_bf16 v[44:47], v[150:153], v[182:185], v[44:47]
	v_mfma_f32_16x16x32_bf16 v[40:43], v[158:161], v[182:185], v[40:43]
	v_mfma_f32_16x16x32_bf16 v[36:39], v[150:153], v[194:197], v[36:39]
	v_mfma_f32_16x16x32_bf16 v[32:35], v[158:161], v[194:197], v[32:35]
	v_mfma_f32_16x16x32_bf16 v[60:63], v[154:157], v[170:173], v[60:63]
	v_mfma_f32_16x16x32_bf16 v[56:59], v[162:165], v[170:173], v[56:59]
	v_mfma_f32_16x16x32_bf16 v[52:55], v[154:157], v[178:181], v[52:55]
	v_mfma_f32_16x16x32_bf16 v[48:51], v[162:165], v[178:181], v[48:51]
	v_mfma_f32_16x16x32_bf16 v[44:47], v[154:157], v[186:189], v[44:47]
	v_mfma_f32_16x16x32_bf16 v[40:43], v[162:165], v[186:189], v[40:43]
	v_mfma_f32_16x16x32_bf16 v[36:39], v[154:157], v[198:201], v[36:39]
	v_mfma_f32_16x16x32_bf16 v[32:35], v[162:165], v[198:201], v[32:35]
	s_setprio 0
	s_barrier
; #define PG8_STAGE(bufoff, gbase, voff) do { _Pragma("unroll") for (int _i = 0; _i < 2; ++_i) \
;         __builtin_amdgcn_global_load_lds((const unsigned*)((const char*)(gbase) + (voff)[_i]), (LAS unsigned*)(lds + (bufoff) + ldsw + _i * 8192), 16, 0, 0); } while (0)
; #define PG8_LDA(dst, b, h) do { _Pragma("unroll") for (int m = 0; m < 4; ++m) _Pragma("unroll") for (int k = 0; k < 2; ++k) dst[m][k] = *(const LAS bf16x8*)(lds + PG8_SA(b, h) + aoff + m * 2048 + k * 1024); } while (0)
; #define PG8_LDB(dst, b, h) do { _Pragma("unroll") for (int n = 0; n < 2; ++n) _Pragma("unroll") for (int k = 0; k < 2; ++k) dst[n][k] = *(const LAS bf16x8*)(lds + PG8_SB(b, h) + boff + n * 2048 + k * 1024); } while (0)
; #define PG8_MMA(ai, bj, At, Bt) do { __builtin_amdgcn_s_setprio(1); _Pragma("unroll") for (int m = 0; m < 4; ++m) _Pragma("unroll") for (int n = 0; n < 2; ++n) _Pragma("unroll") for (int k = 0; k < 2; ++k) \
;         acc[ai][bj][m][n] = __builtin_amdgcn_mfma_f32_16x16x32_bf16(Bt[n][k], At[m][k], acc[ai][bj][m][n], 0, 0, 0); __builtin_amdgcn_s_setprio(0); } while (0)
; #define PG8_WAIT_V(n) asm volatile("s_waitcnt vmcnt(" #n ")" ::: "memory")
; #define PG8_WAIT_L(n) asm volatile("s_waitcnt lgkmcnt(" #n ")" ::: "memory")
; #define PG8_BAR __builtin_amdgcn_s_barrier()
; #define PG8_SCHED __builtin_amdgcn_sched_barrier(0)
; template <class Epi>
; __device__ __forceinline__ void gemm_phase(LAS unsigned char* lds, const Gemm g, const Sched& S, const Epi& E) {
;     ...
;             PG8_STAGE(PG8_SB(0, 1), b2 + hstepB, voffB);
;             PG8_WAIT_V(6); PG8_BAR; PG8_MMA(1, 1, At, B1); PG8_BAR;
;             PG8_LDB(B0, 1, 0); PG8_SCHED; PG8_LDA(At, 1, 0); PG8_STAGE(PG8_SA(0, 1), a2 + hstepA, voffA);
;             PG8_WAIT_L(8); PG8_BAR; PG8_WAIT_L(0); PG8_MMA(0, 0, At, B0); PG8_BAR; PG8_SCHED;
;             PG8_LDB(B1, 1, 1); PG8_STAGE(PG8_SB(1, 0), b3, voffB);
;             PG8_BAR; PG8_WAIT_L(0); PG8_MMA(0, 1, At, B1); PG8_BAR;
;             PG8_LDA(At, 1, 1); PG8_STAGE(PG8_SA(1, 0), a3, voffA);
	s_add_u32 s82, s38, 0x80000
	s_addc_u32 s83, s39, 0
	s_add_i32 s84, s63, s34
	v_lshl_add_u64 v[150:151], s[82:83], 0, v[130:131]
	s_mov_b32 m0, s84
	s_nop 0
	global_load_lds_dwordx4 v[150:151], off
	v_lshl_add_u64 v[150:151], s[82:83], 0, v[128:129]
	s_add_i32 m0, s84, 0x2000
	s_nop 0
	global_load_lds_dwordx4 v[150:151], off
	s_waitcnt vmcnt(6)
	s_barrier
	s_setprio 1
	v_mfma_f32_16x16x32_bf16 v[28:31], v[202:205], v[166:169], v[28:31]
	v_mfma_f32_16x16x32_bf16 v[24:27], v[210:213], v[166:169], v[24:27]
	v_mfma_f32_16x16x32_bf16 v[20:23], v[202:205], v[174:177], v[20:23]
	v_mfma_f32_16x16x32_bf16 v[16:19], v[210:213], v[174:177], v[16:19]
	v_mfma_f32_16x16x32_bf16 v[12:15], v[202:205], v[182:185], v[12:15]
	v_mfma_f32_16x16x32_bf16 v[8:11], v[210:213], v[182:185], v[8:11]
	v_mfma_f32_16x16x32_bf16 v[4:7], v[202:205], v[194:197], v[4:7]
	v_mfma_f32_16x16x32_bf16 v[0:3], v[210:213], v[194:197], v[0:3]
	v_mfma_f32_16x16x32_bf16 v[28:31], v[206:209], v[170:173], v[28:31]
	v_mfma_f32_16x16x32_bf16 v[24:27], v[214:217], v[170:173], v[24:27]
	v_mfma_f32_16x16x32_bf16 v[20:23], v[206:209], v[178:181], v[20:23]
	v_mfma_f32_16x16x32_bf16 v[16:19], v[214:217], v[178:181], v[16:19]
	v_mfma_f32_16x16x32_bf16 v[12:15], v[206:209], v[186:189], v[12:15]
	v_mfma_f32_16x16x32_bf16 v[8:11], v[214:217], v[186:189], v[8:11]
	v_mfma_f32_16x16x32_bf16 v[4:7], v[206:209], v[198:201], v[4:7]
	v_mfma_f32_16x16x32_bf16 v[0:3], v[214:217], v[198:201], v[0:3]
	s_setprio 0
	s_add_i32 s82, 0, 0x18000
	v_add_u32_e32 v162, s82, v148
	s_barrier
	ds_read_b128 v[150:153], v162
	ds_read_b128 v[154:157], v162 offset:1024
	ds_read_b128 v[158:161], v162 offset:2048
	ds_read_b128 v[162:165], v162 offset:3072
	s_add_u32 s54, s54, 0x80000
	s_addc_u32 s55, s55, 0
	s_mov_b32 m0, s53
	v_lshl_add_u64 v[202:203], s[54:55], 0, v[130:131]
	ds_read_b128 v[166:169], v149 offset:32768
	ds_read_b128 v[170:173], v149 offset:33792
	ds_read_b128 v[174:177], v149 offset:34816
	ds_read_b128 v[178:181], v149 offset:35840
	ds_read_b128 v[182:185], v149 offset:36864
	ds_read_b128 v[186:189], v149 offset:37888
	ds_read_b128 v[194:197], v149 offset:38912
	ds_read_b128 v[198:201], v149 offset:39936
	global_load_lds_dwordx4 v[202:203], off
	v_lshl_add_u64 v[202:203], s[54:55], 0, v[128:129]
	s_mov_b32 m0, s56
	s_nop 0
	global_load_lds_dwordx4 v[202:203], off
	s_waitcnt lgkmcnt(8)
	s_barrier
	s_waitcnt lgkmcnt(0)
	s_setprio 1
	s_waitcnt lgkmcnt(0)
	v_mfma_f32_16x16x32_bf16 v[124:127], v[150:153], v[166:169], v[124:127]
	v_mfma_f32_16x16x32_bf16 v[120:123], v[158:161], v[166:169], v[120:123]
	v_mfma_f32_16x16x32_bf16 v[116:119], v[150:153], v[174:177], v[116:119]
	v_mfma_f32_16x16x32_bf16 v[112:115], v[158:161], v[174:177], v[112:115]
	v_mfma_f32_16x16x32_bf16 v[108:111], v[150:153], v[182:185], v[108:111]
	v_mfma_f32_16x16x32_bf16 v[104:107], v[158:161], v[182:185], v[104:107]
	v_mfma_f32_16x16x32_bf16 v[100:103], v[150:153], v[194:197], v[100:103]
	v_mfma_f32_16x16x32_bf16 v[96:99], v[158:161], v[194:197], v[96:99]
	v_mfma_f32_16x16x32_bf16 v[124:127], v[154:157], v[170:173], v[124:127]
	v_mfma_f32_16x16x32_bf16 v[120:123], v[162:165], v[170:173], v[120:123]
	v_mfma_f32_16x16x32_bf16 v[116:119], v[154:157], v[178:181], v[116:119]
	v_mfma_f32_16x16x32_bf16 v[112:115], v[162:165], v[178:181], v[112:115]
	v_mfma_f32_16x16x32_bf16 v[108:111], v[154:157], v[186:189], v[108:111]
	v_mfma_f32_16x16x32_bf16 v[104:107], v[162:165], v[186:189], v[104:107]
	v_mfma_f32_16x16x32_bf16 v[100:103], v[154:157], v[198:201], v[100:103]
	v_mfma_f32_16x16x32_bf16 v[96:99], v[162:165], v[198:201], v[96:99]
	s_setprio 0
	s_barrier
	s_add_i32 s54, 0, 0x1c000
	s_add_i32 s55, s82, s34
	v_add_u32_e32 v214, s54, v148
	v_lshl_add_u64 v[190:191], v[190:191], 0, s[16:17]
	s_mov_b32 m0, s55
	ds_read_b128 v[202:205], v214
	ds_read_b128 v[206:209], v214 offset:1024
	ds_read_b128 v[210:213], v214 offset:2048
	ds_read_b128 v[214:217], v214 offset:3072
	global_load_lds_dwordx4 v[190:191], off
	v_lshl_add_u64 v[190:191], v[218:219], 0, s[16:17]
	s_add_i32 m0, s55, 0x2000
	s_nop 0
	global_load_lds_dwordx4 v[190:191], off
	s_barrier
	s_waitcnt lgkmcnt(0)
	s_setprio 1
	s_waitcnt lgkmcnt(0)
	v_mfma_f32_16x16x32_bf16 v[92:95], v[202:205], v[166:169], v[92:95]
	v_mfma_f32_16x16x32_bf16 v[88:91], v[210:213], v[166:169], v[88:91]
	v_mfma_f32_16x16x32_bf16 v[84:87], v[202:205], v[174:177], v[84:87]
	v_mfma_f32_16x16x32_bf16 v[80:83], v[210:213], v[174:177], v[80:83]
	v_mfma_f32_16x16x32_bf16 v[76:79], v[202:205], v[182:185], v[76:79]
	v_mfma_f32_16x16x32_bf16 v[72:75], v[210:213], v[182:185], v[72:75]
	v_mfma_f32_16x16x32_bf16 v[68:71], v[202:205], v[194:197], v[68:71]
	v_mfma_f32_16x16x32_bf16 v[64:67], v[210:213], v[194:197], v[64:67]
	v_mfma_f32_16x16x32_bf16 v[92:95], v[206:209], v[170:173], v[92:95]
	v_mfma_f32_16x16x32_bf16 v[88:91], v[214:217], v[170:173], v[88:91]
	v_mfma_f32_16x16x32_bf16 v[84:87], v[206:209], v[178:181], v[84:87]
	v_mfma_f32_16x16x32_bf16 v[80:83], v[214:217], v[178:181], v[80:83]
	v_mfma_f32_16x16x32_bf16 v[76:79], v[206:209], v[186:189], v[76:79]
	v_mfma_f32_16x16x32_bf16 v[72:75], v[214:217], v[186:189], v[72:75]
	v_mfma_f32_16x16x32_bf16 v[68:71], v[206:209], v[198:201], v[68:71]
	v_mfma_f32_16x16x32_bf16 v[64:67], v[214:217], v[198:201], v[64:67]
	s_setprio 0
	s_mov_b32 m0, s60
	v_lshl_add_u64 v[190:191], v[220:221], 0, s[16:17]
	s_barrier
	ds_read_b128 v[166:169], v149 offset:49152
	ds_read_b128 v[170:173], v149 offset:50176
	ds_read_b128 v[174:177], v149 offset:51200
	ds_read_b128 v[178:181], v149 offset:52224
	ds_read_b128 v[182:185], v149 offset:53248
	ds_read_b128 v[186:189], v149 offset:54272
	ds_read_b128 v[194:197], v149 offset:55296
	ds_read_b128 v[198:201], v149 offset:56320
	global_load_lds_dwordx4 v[190:191], off
	v_lshl_add_u64 v[190:191], v[222:223], 0, s[16:17]
	s_mov_b32 m0, s61
	s_nop 0
	global_load_lds_dwordx4 v[190:191], off
	s_barrier
; __device__ __forceinline__ unsigned cvt_pk_bf16(float lo, float hi) { unsigned r; asm volatile("v_cvt_pk_bf16_f32 %0, %1, %2" : "=v"(r) : "v"(lo), "v"(hi)); return r; }
; #define PG8_STAGE(bufoff, gbase, voff) do { _Pragma("unroll") for (int _i = 0; _i < 2; ++_i) \
;         __builtin_amdgcn_global_load_lds((const unsigned*)((const char*)(gbase) + (voff)[_i]), (LAS unsigned*)(lds + (bufoff) + ldsw + _i * 8192), 16, 0, 0); } while (0)
; #define PG8_MMA(ai, bj, At, Bt) do { __builtin_amdgcn_s_setprio(1); _Pragma("unroll") for (int m = 0; m < 4; ++m) _Pragma("unroll") for (int n = 0; n < 2; ++n) _Pragma("unroll") for (int k = 0; k < 2; ++k) \
;         acc[ai][bj][m][n] = __builtin_amdgcn_mfma_f32_16x16x32_bf16(Bt[n][k], At[m][k], acc[ai][bj][m][n], 0, 0, 0); __builtin_amdgcn_s_setprio(0); } while (0)
; #define PG8_WAIT_V(n) asm volatile("s_waitcnt vmcnt(" #n ")" ::: "memory")
; #define PG8_WAIT_L(n) asm volatile("s_waitcnt lgkmcnt(" #n ")" ::: "memory")
; #define PG8_BAR __builtin_amdgcn_s_barrier()
; #define PG8_SCHED __builtin_amdgcn_sched_barrier(0)
; template <class Epi>
; __device__ __forceinline__ void gemm_phase(LAS unsigned char* lds, const Gemm g, const Sched& S, const Epi& E) {
;     ...
;             PG8_BAR; PG8_WAIT_L(0); PG8_MMA(1, 0, At, B0); PG8_BAR; PG8_SCHED;
;             PG8_STAGE(PG8_SB(1, 1), b3 + hstepB, voffB);
;             PG8_WAIT_V(6); PG8_BAR; PG8_MMA(1, 1, At, B1); PG8_BAR;
;     __device__ __forceinline__ void operator()(AccRef acc, const Unit& u, int wr, int wc, int fr, int fq) const {
;     ...
;             for (int m = 0; m < 4; ++m) { const size_t row = (size_t)u.pm * 256 + ai * 128 + wr * 64 + m * 16 + fr; float o[8];
; #pragma unroll
;                 for (int bj = 0; bj < 2; ++bj) { const f32x4 gg = acc[ai][bj][m][0], uu = acc[ai][bj][m][1];
; #pragma unroll
;                     for (int j = 0; j < 4; ++j) o[4 * bj + j] = gg[j] * __builtin_amdgcn_rcpf(1.0f + __expf(-gg[j])) * uu[j]; }
;                 u32x4 w; w.x = cvt_pk_bf16(o[0], o[1]); w.y = cvt_pk_bf16(o[2], o[3]); w.z = cvt_pk_bf16(o[4], o[5]); w.w = cvt_pk_bf16(o[6], o[7]);
;                 *(u32x4*)(act + row * FF_ + (u.pn * 4 + wc) * 32 + 8 * fq) = w; }
	s_waitcnt lgkmcnt(0)
	s_setprio 1
	s_waitcnt lgkmcnt(0)
	v_mfma_f32_16x16x32_bf16 v[60:63], v[150:153], v[166:169], v[60:63]
	v_mfma_f32_16x16x32_bf16 v[56:59], v[158:161], v[166:169], v[56:59]
	v_mfma_f32_16x16x32_bf16 v[52:55], v[150:153], v[174:177], v[52:55]
	v_mfma_f32_16x16x32_bf16 v[48:51], v[158:161], v[174:177], v[48:51]
	v_mfma_f32_16x16x32_bf16 v[44:47], v[150:153], v[182:185], v[44:47]
	v_mfma_f32_16x16x32_bf16 v[40:43], v[158:161], v[182:185], v[40:43]
	v_mfma_f32_16x16x32_bf16 v[36:39], v[150:153], v[194:197], v[36:39]
	v_mfma_f32_16x16x32_bf16 v[32:35], v[158:161], v[194:197], v[32:35]
	v_mfma_f32_16x16x32_bf16 v[60:63], v[154:157], v[170:173], v[60:63]
	v_mfma_f32_16x16x32_bf16 v[56:59], v[162:165], v[170:173], v[56:59]
	v_mfma_f32_16x16x32_bf16 v[52:55], v[154:157], v[178:181], v[52:55]
	v_mfma_f32_16x16x32_bf16 v[48:51], v[162:165], v[178:181], v[48:51]
	v_mfma_f32_16x16x32_bf16 v[44:47], v[154:157], v[186:189], v[44:47]
	v_mfma_f32_16x16x32_bf16 v[40:43], v[162:165], v[186:189], v[40:43]
	v_mfma_f32_16x16x32_bf16 v[36:39], v[154:157], v[198:201], v[36:39]
	v_mfma_f32_16x16x32_bf16 v[32:35], v[162:165], v[198:201], v[32:35]
	s_setprio 0
	s_barrier
	s_add_u32 s38, s38, 0x80080
	s_addc_u32 s39, s39, 0
	s_add_i32 s54, s54, s34
	v_lshl_add_u64 v[150:151], s[38:39], 0, v[130:131]
	s_mov_b32 m0, s54
	s_nop 0
	global_load_lds_dwordx4 v[150:151], off
	v_lshl_add_u64 v[150:151], s[38:39], 0, v[128:129]
	s_add_i32 m0, s54, 0x2000
	s_nop 0
	global_load_lds_dwordx4 v[150:151], off
	s_waitcnt vmcnt(6)
	s_barrier
	s_setprio 1
	v_mfma_f32_16x16x32_bf16 v[28:31], v[202:205], v[166:169], v[28:31]
	v_mfma_f32_16x16x32_bf16 v[24:27], v[210:213], v[166:169], v[24:27]
	v_mfma_f32_16x16x32_bf16 v[20:23], v[202:205], v[174:177], v[20:23]
	v_mfma_f32_16x16x32_bf16 v[16:19], v[210:213], v[174:177], v[16:19]
	v_mfma_f32_16x16x32_bf16 v[12:15], v[202:205], v[182:185], v[12:15]
	v_mfma_f32_16x16x32_bf16 v[8:11], v[210:213], v[182:185], v[8:11]
	v_mfma_f32_16x16x32_bf16 v[4:7], v[202:205], v[194:197], v[4:7]
	v_mfma_f32_16x16x32_bf16 v[0:3], v[210:213], v[194:197], v[0:3]
	v_mfma_f32_16x16x32_bf16 v[28:31], v[206:209], v[170:173], v[28:31]
	v_mfma_f32_16x16x32_bf16 v[24:27], v[214:217], v[170:173], v[24:27]
	v_mfma_f32_16x16x32_bf16 v[20:23], v[206:209], v[178:181], v[20:23]
	v_mfma_f32_16x16x32_bf16 v[16:19], v[214:217], v[178:181], v[16:19]
	v_mfma_f32_16x16x32_bf16 v[12:15], v[206:209], v[186:189], v[12:15]
	v_mfma_f32_16x16x32_bf16 v[8:11], v[214:217], v[186:189], v[8:11]
	v_mfma_f32_16x16x32_bf16 v[4:7], v[206:209], v[198:201], v[4:7]
	v_mfma_f32_16x16x32_bf16 v[0:3], v[214:217], v[198:201], v[0:3]
	s_setprio 0
	s_add_i32 s81, s81, 2
	s_add_u32 s36, s36, 0x100
	s_addc_u32 s37, s37, 0
	s_cmp_gt_u32 s81, 29
	s_barrier
	s_cbranch_scc0 .LBB0_2088
	v_mov_b32_e32 v170, 0xbfb8aa3b
	v_mov_b32_e32 v172, 1.0
	v_mov_b64_e32 v[176:177], 0
	v_mov_b64_e32 v[178:179], 0
	s_add_u32 s36, s13, 0xffffff00
	s_addc_u32 s37, s51, -1
	s_ashr_i32 s13, s12, 31
	s_lshl_b64 s[38:39], s[12:13], 8
	v_lshl_add_u64 v[144:145], v[134:135], 0, s[38:39]
	v_mov_b64_e32 v[146:147], s[44:45]
	v_mad_u64_u32 v[146:147], s[54:55], v144, s64, v[146:147]
	s_lshl_b32 s13, s58, 7
	v_mov_b32_e32 v144, v147
	s_or_b32 s38, s13, s59
	v_mad_u64_u32 v[144:145], s[54:55], v145, s64, v[144:145]
	s_ashr_i32 s39, s38, 31
	v_mov_b32_e32 v147, v144
	v_lshl_add_u64 v[144:145], s[38:39], 1, v[146:147]
	v_lshl_add_u64 v[144:145], v[144:145], 0, v[132:133]
	v_pk_mul_f32 v[162:163], v[124:125], v[170:171] op_sel_hi:[1,0]
	v_pk_mul_f32 v[164:165], v[126:127], v[170:171] op_sel_hi:[1,0]
	v_pk_mul_f32 v[166:167], v[92:93], v[170:171] op_sel_hi:[1,0]
	v_pk_mul_f32 v[168:169], v[94:95], v[170:171] op_sel_hi:[1,0]
	v_exp_f32_e32 v162, v162
	v_exp_f32_e32 v163, v163
	v_exp_f32_e32 v164, v164
	v_exp_f32_e32 v165, v165
	v_exp_f32_e32 v166, v166
	v_exp_f32_e32 v167, v167
	v_exp_f32_e32 v168, v168
	v_exp_f32_e32 v169, v169
	v_pk_add_f32 v[162:163], v[162:163], v[172:173] op_sel_hi:[1,0]
	v_pk_add_f32 v[164:165], v[164:165], v[172:173] op_sel_hi:[1,0]
	v_pk_add_f32 v[166:167], v[166:167], v[172:173] op_sel_hi:[1,0]
	v_pk_add_f32 v[168:169], v[168:169], v[172:173] op_sel_hi:[1,0]
	v_rcp_f32_e32 v162, v162
	v_rcp_f32_e32 v163, v163
	v_rcp_f32_e32 v164, v164
	v_rcp_f32_e32 v165, v165
	v_rcp_f32_e32 v166, v166
	v_rcp_f32_e32 v167, v167
	v_rcp_f32_e32 v168, v168
	v_rcp_f32_e32 v169, v169
	v_pk_mul_f32 v[162:163], v[124:125], v[162:163]
	v_pk_mul_f32 v[164:165], v[126:127], v[164:165]
	v_pk_mul_f32 v[166:167], v[92:93], v[166:167]
	v_pk_mul_f32 v[168:169], v[94:95], v[168:169]
	v_pk_mul_f32 v[162:163], v[120:121], v[162:163]
	v_pk_mul_f32 v[164:165], v[122:123], v[164:165]
	v_pk_mul_f32 v[166:167], v[88:89], v[166:167]
	v_pk_mul_f32 v[168:169], v[90:91], v[168:169]
	v_cvt_pk_bf16_f32 v150, v162, v163
	v_cvt_pk_bf16_f32 v151, v164, v165
	v_cvt_pk_bf16_f32 v152, v166, v167
	v_cvt_pk_bf16_f32 v153, v168, v169
	global_store_dwordx4 v[144:145], v[150:153], off nt
	v_add_co_u32_e32 v146, vcc, s65, v144
	s_nop 0
	v_addc_co_u32_e32 v147, vcc, 0, v145, vcc
	v_pk_mul_f32 v[162:163], v[116:117], v[170:171] op_sel_hi:[1,0]
	v_pk_mul_f32 v[164:165], v[118:119], v[170:171] op_sel_hi:[1,0]
	v_pk_mul_f32 v[166:167], v[84:85], v[170:171] op_sel_hi:[1,0]
	v_pk_mul_f32 v[168:169], v[86:87], v[170:171] op_sel_hi:[1,0]
	v_exp_f32_e32 v162, v162
	v_exp_f32_e32 v163, v163
	v_exp_f32_e32 v164, v164
	v_exp_f32_e32 v165, v165
	v_exp_f32_e32 v166, v166
	v_exp_f32_e32 v167, v167
	v_exp_f32_e32 v168, v168
	v_exp_f32_e32 v169, v169
	v_pk_add_f32 v[162:163], v[162:163], v[172:173] op_sel_hi:[1,0]
	v_pk_add_f32 v[164:165], v[164:165], v[172:173] op_sel_hi:[1,0]
; __device__ __forceinline__ unsigned cvt_pk_bf16(float lo, float hi) { unsigned r; asm volatile("v_cvt_pk_bf16_f32 %0, %1, %2" : "=v"(r) : "v"(lo), "v"(hi)); return r; }
;     __device__ __forceinline__ void operator()(AccRef acc, const Unit& u, int wr, int wc, int fr, int fq) const {
;     ...
;             for (int m = 0; m < 4; ++m) { const size_t row = (size_t)u.pm * 256 + ai * 128 + wr * 64 + m * 16 + fr; float o[8];
; #pragma unroll
;                 for (int bj = 0; bj < 2; ++bj) { const f32x4 gg = acc[ai][bj][m][0], uu = acc[ai][bj][m][1];
; #pragma unroll
;                     for (int j = 0; j < 4; ++j) o[4 * bj + j] = gg[j] * __builtin_amdgcn_rcpf(1.0f + __expf(-gg[j])) * uu[j]; }
;                 u32x4 w; w.x = cvt_pk_bf16(o[0], o[1]); w.y = cvt_pk_bf16(o[2], o[3]); w.z = cvt_pk_bf16(o[4], o[5]); w.w = cvt_pk_bf16(o[6], o[7]);
;                 *(u32x4*)(act + row * FF_ + (u.pn * 4 + wc) * 32 + 8 * fq) = w; }
	v_pk_add_f32 v[166:167], v[166:167], v[172:173] op_sel_hi:[1,0]
	v_pk_add_f32 v[168:169], v[168:169], v[172:173] op_sel_hi:[1,0]
	v_rcp_f32_e32 v162, v162
	v_rcp_f32_e32 v163, v163
	v_rcp_f32_e32 v164, v164
	v_rcp_f32_e32 v165, v165
	v_rcp_f32_e32 v166, v166
	v_rcp_f32_e32 v167, v167
	v_rcp_f32_e32 v168, v168
	v_rcp_f32_e32 v169, v169
	v_pk_mul_f32 v[162:163], v[116:117], v[162:163]
	v_pk_mul_f32 v[164:165], v[118:119], v[164:165]
	v_pk_mul_f32 v[166:167], v[84:85], v[166:167]
	v_pk_mul_f32 v[168:169], v[86:87], v[168:169]
	v_pk_mul_f32 v[162:163], v[112:113], v[162:163]
	v_pk_mul_f32 v[164:165], v[114:115], v[164:165]
	v_pk_mul_f32 v[166:167], v[80:81], v[166:167]
	v_pk_mul_f32 v[168:169], v[82:83], v[168:169]
	v_cvt_pk_bf16_f32 v150, v162, v163
	v_cvt_pk_bf16_f32 v151, v164, v165
	v_cvt_pk_bf16_f32 v152, v166, v167
	v_cvt_pk_bf16_f32 v153, v168, v169
	global_store_dwordx4 v[146:147], v[150:153], off nt
	v_mfma_f32_32x32x16_bf16 v[80:95], v[176:179], v[176:179], 0
	v_mfma_f32_32x32x16_bf16 v[112:127], v[176:179], v[176:179], 0
	v_add_co_u32_e32 v146, vcc, s66, v144
	s_nop 0
	v_addc_co_u32_e32 v147, vcc, 0, v145, vcc
	v_pk_mul_f32 v[162:163], v[108:109], v[170:171] op_sel_hi:[1,0]
	v_pk_mul_f32 v[164:165], v[110:111], v[170:171] op_sel_hi:[1,0]
	v_pk_mul_f32 v[166:167], v[76:77], v[170:171] op_sel_hi:[1,0]
	v_pk_mul_f32 v[168:169], v[78:79], v[170:171] op_sel_hi:[1,0]
	v_exp_f32_e32 v162, v162
	v_exp_f32_e32 v163, v163
	v_exp_f32_e32 v164, v164
	v_exp_f32_e32 v165, v165
	v_exp_f32_e32 v166, v166
	v_exp_f32_e32 v167, v167
	v_exp_f32_e32 v168, v168
	v_exp_f32_e32 v169, v169
	v_pk_add_f32 v[162:163], v[162:163], v[172:173] op_sel_hi:[1,0]
	v_pk_add_f32 v[164:165], v[164:165], v[172:173] op_sel_hi:[1,0]
	v_pk_add_f32 v[166:167], v[166:167], v[172:173] op_sel_hi:[1,0]
	v_pk_add_f32 v[168:169], v[168:169], v[172:173] op_sel_hi:[1,0]
	v_rcp_f32_e32 v162, v162
	v_rcp_f32_e32 v163, v163
	v_rcp_f32_e32 v164, v164
	v_rcp_f32_e32 v165, v165
	v_rcp_f32_e32 v166, v166
	v_rcp_f32_e32 v167, v167
	v_rcp_f32_e32 v168, v168
	v_rcp_f32_e32 v169, v169
	v_pk_mul_f32 v[162:163], v[108:109], v[162:163]
	v_pk_mul_f32 v[164:165], v[110:111], v[164:165]
	v_pk_mul_f32 v[166:167], v[76:77], v[166:167]
	v_pk_mul_f32 v[168:169], v[78:79], v[168:169]
	v_pk_mul_f32 v[162:163], v[104:105], v[162:163]
	v_pk_mul_f32 v[164:165], v[106:107], v[164:165]
	v_pk_mul_f32 v[166:167], v[72:73], v[166:167]
	v_pk_mul_f32 v[168:169], v[74:75], v[168:169]
	v_cvt_pk_bf16_f32 v150, v162, v163
	v_cvt_pk_bf16_f32 v151, v164, v165
	v_cvt_pk_bf16_f32 v152, v166, v167
	v_cvt_pk_bf16_f32 v153, v168, v169
	global_store_dwordx4 v[146:147], v[150:153], off nt
	v_add_co_u32_e32 v146, vcc, s67, v144
	s_nop 0
	v_addc_co_u32_e32 v147, vcc, 0, v145, vcc
	v_pk_mul_f32 v[162:163], v[100:101], v[170:171] op_sel_hi:[1,0]
	v_pk_mul_f32 v[164:165], v[102:103], v[170:171] op_sel_hi:[1,0]
	v_pk_mul_f32 v[166:167], v[68:69], v[170:171] op_sel_hi:[1,0]
	v_pk_mul_f32 v[168:169], v[70:71], v[170:171] op_sel_hi:[1,0]
	v_exp_f32_e32 v162, v162
	v_exp_f32_e32 v163, v163
	v_exp_f32_e32 v164, v164
	v_exp_f32_e32 v165, v165
	v_exp_f32_e32 v166, v166
	v_exp_f32_e32 v167, v167
	v_exp_f32_e32 v168, v168
	v_exp_f32_e32 v169, v169
	v_pk_add_f32 v[162:163], v[162:163], v[172:173] op_sel_hi:[1,0]
	v_pk_add_f32 v[164:165], v[164:165], v[172:173] op_sel_hi:[1,0]
	v_pk_add_f32 v[166:167], v[166:167], v[172:173] op_sel_hi:[1,0]
	v_pk_add_f32 v[168:169], v[168:169], v[172:173] op_sel_hi:[1,0]
	v_rcp_f32_e32 v162, v162
	v_rcp_f32_e32 v163, v163
	v_rcp_f32_e32 v164, v164
	v_rcp_f32_e32 v165, v165
	v_rcp_f32_e32 v166, v166
	v_rcp_f32_e32 v167, v167
	v_rcp_f32_e32 v168, v168
	v_rcp_f32_e32 v169, v169
	v_pk_mul_f32 v[162:163], v[100:101], v[162:163]
	v_pk_mul_f32 v[164:165], v[102:103], v[164:165]
	v_pk_mul_f32 v[166:167], v[68:69], v[166:167]
	v_pk_mul_f32 v[168:169], v[70:71], v[168:169]
	v_pk_mul_f32 v[162:163], v[96:97], v[162:163]
	v_pk_mul_f32 v[164:165], v[98:99], v[164:165]
	v_pk_mul_f32 v[166:167], v[64:65], v[166:167]
	v_pk_mul_f32 v[168:169], v[66:67], v[168:169]
	v_cvt_pk_bf16_f32 v150, v162, v163
	v_cvt_pk_bf16_f32 v151, v164, v165
	v_cvt_pk_bf16_f32 v152, v166, v167
	v_cvt_pk_bf16_f32 v153, v168, v169
	global_store_dwordx4 v[146:147], v[150:153], off nt
	v_mfma_f32_32x32x16_bf16 v[64:79], v[176:179], v[176:179], 0
	v_mfma_f32_32x32x16_bf16 v[96:111], v[176:179], v[176:179], 0
	v_add_co_u32_e32 v146, vcc, s70, v144
	s_nop 0
	v_addc_co_u32_e32 v147, vcc, 0, v145, vcc
	v_pk_mul_f32 v[162:163], v[60:61], v[170:171] op_sel_hi:[1,0]
	v_pk_mul_f32 v[164:165], v[62:63], v[170:171] op_sel_hi:[1,0]
	v_pk_mul_f32 v[166:167], v[28:29], v[170:171] op_sel_hi:[1,0]
	v_pk_mul_f32 v[168:169], v[30:31], v[170:171] op_sel_hi:[1,0]
	v_exp_f32_e32 v162, v162
	v_exp_f32_e32 v163, v163
	v_exp_f32_e32 v164, v164
	v_exp_f32_e32 v165, v165
	v_exp_f32_e32 v166, v166
	v_exp_f32_e32 v167, v167
	v_exp_f32_e32 v168, v168
	v_exp_f32_e32 v169, v169
	v_pk_add_f32 v[162:163], v[162:163], v[172:173] op_sel_hi:[1,0]
	v_pk_add_f32 v[164:165], v[164:165], v[172:173] op_sel_hi:[1,0]
	v_pk_add_f32 v[166:167], v[166:167], v[172:173] op_sel_hi:[1,0]
	v_pk_add_f32 v[168:169], v[168:169], v[172:173] op_sel_hi:[1,0]
	v_rcp_f32_e32 v162, v162
	v_rcp_f32_e32 v163, v163
	v_rcp_f32_e32 v164, v164
	v_rcp_f32_e32 v165, v165
	v_rcp_f32_e32 v166, v166
	v_rcp_f32_e32 v167, v167
	v_rcp_f32_e32 v168, v168
	v_rcp_f32_e32 v169, v169
	v_pk_mul_f32 v[162:163], v[60:61], v[162:163]
	v_pk_mul_f32 v[164:165], v[62:63], v[164:165]
	v_pk_mul_f32 v[166:167], v[28:29], v[166:167]
	v_pk_mul_f32 v[168:169], v[30:31], v[168:169]
; __device__ __forceinline__ unsigned cvt_pk_bf16(float lo, float hi) { unsigned r; asm volatile("v_cvt_pk_bf16_f32 %0, %1, %2" : "=v"(r) : "v"(lo), "v"(hi)); return r; }
; template <class Epi>
; __device__ __forceinline__ void gemm_phase(LAS unsigned char* lds, const Gemm g, const Sched& S, const Epi& E) {
;     ...
;         if (!has_next) break;
; #pragma unroll
;         for (int a = 0; a < 2; ++a)
; #pragma unroll
;             for (int b = 0; b < 2; ++b)
; #pragma unroll
;                 for (int m = 0; m < 4; ++m)
; #pragma unroll
;                     for (int n = 0; n < 2; ++n) acc[a][b][m][n] = (f32x4){0.f, 0.f, 0.f, 0.f};
;         cur = nxt; cA = nA; cB = nB; ++ui;
;     __device__ __forceinline__ void operator()(AccRef acc, const Unit& u, int wr, int wc, int fr, int fq) const {
;     ...
;             for (int m = 0; m < 4; ++m) { const size_t row = (size_t)u.pm * 256 + ai * 128 + wr * 64 + m * 16 + fr; float o[8];
; #pragma unroll
;                 for (int bj = 0; bj < 2; ++bj) { const f32x4 gg = acc[ai][bj][m][0], uu = acc[ai][bj][m][1];
; #pragma unroll
;                     for (int j = 0; j < 4; ++j) o[4 * bj + j] = gg[j] * __builtin_amdgcn_rcpf(1.0f + __expf(-gg[j])) * uu[j]; }
;                 u32x4 w; w.x = cvt_pk_bf16(o[0], o[1]); w.y = cvt_pk_bf16(o[2], o[3]); w.z = cvt_pk_bf16(o[4], o[5]); w.w = cvt_pk_bf16(o[6], o[7]);
;                 *(u32x4*)(act + row * FF_ + (u.pn * 4 + wc) * 32 + 8 * fq) = w; }
	v_pk_mul_f32 v[162:163], v[56:57], v[162:163]
	v_pk_mul_f32 v[164:165], v[58:59], v[164:165]
	v_pk_mul_f32 v[166:167], v[24:25], v[166:167]
	v_pk_mul_f32 v[168:169], v[26:27], v[168:169]
	v_cvt_pk_bf16_f32 v150, v162, v163
	v_cvt_pk_bf16_f32 v151, v164, v165
	v_cvt_pk_bf16_f32 v152, v166, v167
	v_cvt_pk_bf16_f32 v153, v168, v169
	global_store_dwordx4 v[146:147], v[150:153], off nt
	v_add_co_u32_e32 v146, vcc, s71, v144
	s_nop 0
	v_addc_co_u32_e32 v147, vcc, 0, v145, vcc
	v_pk_mul_f32 v[162:163], v[52:53], v[170:171] op_sel_hi:[1,0]
	v_pk_mul_f32 v[164:165], v[54:55], v[170:171] op_sel_hi:[1,0]
	v_pk_mul_f32 v[166:167], v[20:21], v[170:171] op_sel_hi:[1,0]
	v_pk_mul_f32 v[168:169], v[22:23], v[170:171] op_sel_hi:[1,0]
	v_exp_f32_e32 v162, v162
	v_exp_f32_e32 v163, v163
	v_exp_f32_e32 v164, v164
	v_exp_f32_e32 v165, v165
	v_exp_f32_e32 v166, v166
	v_exp_f32_e32 v167, v167
	v_exp_f32_e32 v168, v168
	v_exp_f32_e32 v169, v169
	v_pk_add_f32 v[162:163], v[162:163], v[172:173] op_sel_hi:[1,0]
	v_pk_add_f32 v[164:165], v[164:165], v[172:173] op_sel_hi:[1,0]
	v_pk_add_f32 v[166:167], v[166:167], v[172:173] op_sel_hi:[1,0]
	v_pk_add_f32 v[168:169], v[168:169], v[172:173] op_sel_hi:[1,0]
	v_rcp_f32_e32 v162, v162
	v_rcp_f32_e32 v163, v163
	v_rcp_f32_e32 v164, v164
	v_rcp_f32_e32 v165, v165
	v_rcp_f32_e32 v166, v166
	v_rcp_f32_e32 v167, v167
	v_rcp_f32_e32 v168, v168
	v_rcp_f32_e32 v169, v169
	v_pk_mul_f32 v[162:163], v[52:53], v[162:163]
	v_pk_mul_f32 v[164:165], v[54:55], v[164:165]
	v_pk_mul_f32 v[166:167], v[20:21], v[166:167]
	v_pk_mul_f32 v[168:169], v[22:23], v[168:169]
	v_pk_mul_f32 v[162:163], v[48:49], v[162:163]
	v_pk_mul_f32 v[164:165], v[50:51], v[164:165]
	v_pk_mul_f32 v[166:167], v[16:17], v[166:167]
	v_pk_mul_f32 v[168:169], v[18:19], v[168:169]
	v_cvt_pk_bf16_f32 v150, v162, v163
	v_cvt_pk_bf16_f32 v151, v164, v165
	v_cvt_pk_bf16_f32 v152, v166, v167
	v_cvt_pk_bf16_f32 v153, v168, v169
	global_store_dwordx4 v[146:147], v[150:153], off nt
	v_mfma_f32_32x32x16_bf16 v[16:31], v[176:179], v[176:179], 0
	v_mfma_f32_32x32x16_bf16 v[48:63], v[176:179], v[176:179], 0
	v_add_co_u32_e32 v146, vcc, s78, v144
	s_nop 0
	v_addc_co_u32_e32 v147, vcc, 0, v145, vcc
	v_pk_mul_f32 v[162:163], v[44:45], v[170:171] op_sel_hi:[1,0]
	v_pk_mul_f32 v[164:165], v[46:47], v[170:171] op_sel_hi:[1,0]
	v_pk_mul_f32 v[166:167], v[12:13], v[170:171] op_sel_hi:[1,0]
	v_pk_mul_f32 v[168:169], v[14:15], v[170:171] op_sel_hi:[1,0]
	v_exp_f32_e32 v162, v162
	v_exp_f32_e32 v163, v163
	v_exp_f32_e32 v164, v164
	v_exp_f32_e32 v165, v165
	v_exp_f32_e32 v166, v166
	v_exp_f32_e32 v167, v167
	v_exp_f32_e32 v168, v168
	v_exp_f32_e32 v169, v169
	v_pk_add_f32 v[162:163], v[162:163], v[172:173] op_sel_hi:[1,0]
	v_pk_add_f32 v[164:165], v[164:165], v[172:173] op_sel_hi:[1,0]
	v_pk_add_f32 v[166:167], v[166:167], v[172:173] op_sel_hi:[1,0]
	v_pk_add_f32 v[168:169], v[168:169], v[172:173] op_sel_hi:[1,0]
	v_rcp_f32_e32 v162, v162
	v_rcp_f32_e32 v163, v163
	v_rcp_f32_e32 v164, v164
	v_rcp_f32_e32 v165, v165
	v_rcp_f32_e32 v166, v166
	v_rcp_f32_e32 v167, v167
	v_rcp_f32_e32 v168, v168
	v_rcp_f32_e32 v169, v169
	v_pk_mul_f32 v[162:163], v[44:45], v[162:163]
	v_pk_mul_f32 v[164:165], v[46:47], v[164:165]
	v_pk_mul_f32 v[166:167], v[12:13], v[166:167]
	v_pk_mul_f32 v[168:169], v[14:15], v[168:169]
	v_pk_mul_f32 v[162:163], v[40:41], v[162:163]
	v_pk_mul_f32 v[164:165], v[42:43], v[164:165]
	v_pk_mul_f32 v[166:167], v[8:9], v[166:167]
	v_pk_mul_f32 v[168:169], v[10:11], v[168:169]
	v_cvt_pk_bf16_f32 v150, v162, v163
	v_cvt_pk_bf16_f32 v151, v164, v165
	v_cvt_pk_bf16_f32 v152, v166, v167
	v_cvt_pk_bf16_f32 v153, v168, v169
	global_store_dwordx4 v[146:147], v[150:153], off nt
	v_add_co_u32_e32 v144, vcc, 0x1e4000, v144
	v_addc_co_u32_e32 v145, vcc, 0, v145, vcc
	s_andn2_b64 vcc, exec, s[10:11]
	v_pk_mul_f32 v[162:163], v[36:37], v[170:171] op_sel_hi:[1,0]
	v_pk_mul_f32 v[164:165], v[38:39], v[170:171] op_sel_hi:[1,0]
	v_pk_mul_f32 v[166:167], v[4:5], v[170:171] op_sel_hi:[1,0]
	v_pk_mul_f32 v[168:169], v[6:7], v[170:171] op_sel_hi:[1,0]
	v_exp_f32_e32 v162, v162
	v_exp_f32_e32 v163, v163
	v_exp_f32_e32 v164, v164
	v_exp_f32_e32 v165, v165
	v_exp_f32_e32 v166, v166
	v_exp_f32_e32 v167, v167
	v_exp_f32_e32 v168, v168
	v_exp_f32_e32 v169, v169
	v_pk_add_f32 v[162:163], v[162:163], v[172:173] op_sel_hi:[1,0]
	v_pk_add_f32 v[164:165], v[164:165], v[172:173] op_sel_hi:[1,0]
	v_pk_add_f32 v[166:167], v[166:167], v[172:173] op_sel_hi:[1,0]
	v_pk_add_f32 v[168:169], v[168:169], v[172:173] op_sel_hi:[1,0]
	v_rcp_f32_e32 v162, v162
	v_rcp_f32_e32 v163, v163
	v_rcp_f32_e32 v164, v164
	v_rcp_f32_e32 v165, v165
	v_rcp_f32_e32 v166, v166
	v_rcp_f32_e32 v167, v167
	v_rcp_f32_e32 v168, v168
	v_rcp_f32_e32 v169, v169
	v_pk_mul_f32 v[162:163], v[36:37], v[162:163]
	v_pk_mul_f32 v[164:165], v[38:39], v[164:165]
	v_pk_mul_f32 v[166:167], v[4:5], v[166:167]
	v_pk_mul_f32 v[168:169], v[6:7], v[168:169]
	v_pk_mul_f32 v[162:163], v[32:33], v[162:163]
	v_pk_mul_f32 v[164:165], v[34:35], v[164:165]
	v_pk_mul_f32 v[166:167], v[0:1], v[166:167]
	v_pk_mul_f32 v[168:169], v[2:3], v[168:169]
	v_cvt_pk_bf16_f32 v150, v162, v163
	v_cvt_pk_bf16_f32 v151, v164, v165
	v_cvt_pk_bf16_f32 v152, v166, v167
	v_cvt_pk_bf16_f32 v153, v168, v169
	global_store_dwordx4 v[144:145], v[150:153], off nt
	v_mfma_f32_32x32x16_bf16 v[0:15], v[176:179], v[176:179], 0
	v_mfma_f32_32x32x16_bf16 v[32:47], v[176:179], v[176:179], 0
	s_cbranch_vccz .LBB0_2084
	s_mov_b64 s[22:23], s[36:37]
	s_andn2_b64 vcc, exec, s[8:9]
	s_mov_b64 s[36:37], s[22:23]
	s_cbranch_vccnz .LBB0_2085

; #define PG8_STAGE(bufoff, gbase, voff) do { _Pragma("unroll") for (int _i = 0; _i < 2; ++_i) \
;         __builtin_amdgcn_global_load_lds((const unsigned*)((const char*)(gbase) + (voff)[_i]), (LAS unsigned*)(lds + (bufoff) + ldsw + _i * 8192), 16, 0, 0); } while (0)
; #define PG8_LDA(dst, b, h) do { _Pragma("unroll") for (int m = 0; m < 4; ++m) _Pragma("unroll") for (int k = 0; k < 2; ++k) dst[m][k] = *(const LAS bf16x8*)(lds + PG8_SA(b, h) + aoff + m * 2048 + k * 1024); } while (0)
; #define PG8_LDB(dst, b, h) do { _Pragma("unroll") for (int n = 0; n < 2; ++n) _Pragma("unroll") for (int k = 0; k < 2; ++k) dst[n][k] = *(const LAS bf16x8*)(lds + PG8_SB(b, h) + boff + n * 2048 + k * 1024); } while (0)
; #define PG8_MMA(ai, bj, At, Bt) do { __builtin_amdgcn_s_setprio(1); _Pragma("unroll") for (int m = 0; m < 4; ++m) _Pragma("unroll") for (int n = 0; n < 2; ++n) _Pragma("unroll") for (int k = 0; k < 2; ++k) \
;         acc[ai][bj][m][n] = __builtin_amdgcn_mfma_f32_16x16x32_bf16(Bt[n][k], At[m][k], acc[ai][bj][m][n], 0, 0, 0); __builtin_amdgcn_s_setprio(0); } while (0)
; #define PG8_WAIT_L(n) asm volatile("s_waitcnt lgkmcnt(" #n ")" ::: "memory")
; #define PG8_BAR __builtin_amdgcn_s_barrier()
; #define PG8_SCHED __builtin_amdgcn_sched_barrier(0)
; template <class Epi>
; __device__ __forceinline__ void gemm_phase(LAS unsigned char* lds, const Gemm g, const Sched& S, const Epi& E) {
;     ...
;             PG8_LDB(B0, 0, 0); PG8_SCHED; PG8_LDA(At, 0, 0); PG8_STAGE(PG8_SA(1, 1), a1 + hstepA, voffA);
;             PG8_WAIT_L(8); PG8_BAR; PG8_WAIT_L(0); PG8_MMA(0, 0, At, B0); PG8_BAR; PG8_SCHED;
;             PG8_LDB(B1, 0, 1); PG8_STAGE(PG8_SB(0, 0), b2, voffB);
;             PG8_BAR; PG8_WAIT_L(0); PG8_MMA(0, 1, At, B1); PG8_BAR;
;             PG8_LDA(At, 0, 1); PG8_STAGE(PG8_SA(0, 0), a2, voffA);
;             PG8_BAR; PG8_WAIT_L(0); PG8_MMA(1, 0, At, B0); PG8_BAR; PG8_SCHED;
.LBB0_3085:
	v_add_u32_e32 v162, s54, v148
	s_add_u32 s36, s12, s24
	ds_read_b128 v[150:153], v162
	ds_read_b128 v[154:157], v162 offset:1024
	ds_read_b128 v[158:161], v162 offset:2048
	ds_read_b128 v[162:165], v162 offset:3072
	s_addc_u32 s37, s13, s25
	s_add_u32 s36, s36, 0x100
	s_addc_u32 s37, s37, 0
	s_add_u32 s70, s11, s24
	s_addc_u32 s71, s64, s25
	s_cmpk_eq_i32 s24, 0xf00
	s_cselect_b32 s39, s19, s37
	s_cselect_b32 s38, s65, s36
	s_cselect_b32 s37, s17, s71
	s_cselect_b32 s36, s66, s70
	v_lshl_add_u64 v[190:191], v[144:145], 0, s[24:25]
	s_add_i32 m0, s40, 0xc000
	ds_read_b128 v[166:169], v149
	ds_read_b128 v[170:173], v149 offset:1024
	ds_read_b128 v[174:177], v149 offset:2048
	ds_read_b128 v[178:181], v149 offset:3072
	ds_read_b128 v[182:185], v149 offset:4096
	ds_read_b128 v[186:189], v149 offset:5120
	ds_read_b128 v[194:197], v149 offset:6144
	ds_read_b128 v[198:201], v149 offset:7168
	global_load_lds_dwordx4 v[190:191], off
	v_lshl_add_u64 v[190:191], v[146:147], 0, s[24:25]
	s_add_i32 m0, s40, 0xe000
	s_nop 0
	global_load_lds_dwordx4 v[190:191], off
	s_waitcnt lgkmcnt(8)
	s_barrier
	s_waitcnt lgkmcnt(0)
	s_setprio 1
	s_waitcnt lgkmcnt(0)
	v_mfma_f32_16x16x32_bf16 v[124:127], v[150:153], v[166:169], v[124:127]
	v_mfma_f32_16x16x32_bf16 v[120:123], v[158:161], v[166:169], v[120:123]
	v_mfma_f32_16x16x32_bf16 v[116:119], v[150:153], v[174:177], v[116:119]
	v_mfma_f32_16x16x32_bf16 v[112:115], v[158:161], v[174:177], v[112:115]
	v_mfma_f32_16x16x32_bf16 v[108:111], v[150:153], v[182:185], v[108:111]
	v_mfma_f32_16x16x32_bf16 v[104:107], v[158:161], v[182:185], v[104:107]
	v_mfma_f32_16x16x32_bf16 v[100:103], v[150:153], v[194:197], v[100:103]
	v_mfma_f32_16x16x32_bf16 v[96:99], v[158:161], v[194:197], v[96:99]
	v_mfma_f32_16x16x32_bf16 v[124:127], v[154:157], v[170:173], v[124:127]
	v_mfma_f32_16x16x32_bf16 v[120:123], v[162:165], v[170:173], v[120:123]
	v_mfma_f32_16x16x32_bf16 v[116:119], v[154:157], v[178:181], v[116:119]
	v_mfma_f32_16x16x32_bf16 v[112:115], v[162:165], v[178:181], v[112:115]
	v_mfma_f32_16x16x32_bf16 v[108:111], v[154:157], v[186:189], v[108:111]
	v_mfma_f32_16x16x32_bf16 v[104:107], v[162:165], v[186:189], v[104:107]
	v_mfma_f32_16x16x32_bf16 v[100:103], v[154:157], v[198:201], v[100:103]
	v_mfma_f32_16x16x32_bf16 v[96:99], v[162:165], v[198:201], v[96:99]
	s_setprio 0
	s_barrier
	v_add_u32_e32 v190, s55, v148
	s_add_i32 s70, s54, s34
	ds_read_b128 v[202:205], v190
	ds_read_b128 v[206:209], v190 offset:1024
	ds_read_b128 v[210:213], v190 offset:2048
	ds_read_b128 v[214:217], v190 offset:3072
	v_lshl_add_u64 v[190:191], s[36:37], 0, v[130:131]
	s_mov_b32 m0, s70
	v_lshl_add_u64 v[218:219], s[36:37], 0, v[128:129]
	global_load_lds_dwordx4 v[190:191], off
	s_add_i32 m0, s70, 0x2000
	s_nop 0
	global_load_lds_dwordx4 v[218:219], off
	s_barrier
	s_waitcnt lgkmcnt(0)
	s_setprio 1
	s_waitcnt lgkmcnt(0)
	v_mfma_f32_16x16x32_bf16 v[92:95], v[202:205], v[166:169], v[92:95]
	v_mfma_f32_16x16x32_bf16 v[88:91], v[210:213], v[166:169], v[88:91]
	v_mfma_f32_16x16x32_bf16 v[84:87], v[202:205], v[174:177], v[84:87]
	v_mfma_f32_16x16x32_bf16 v[80:83], v[210:213], v[174:177], v[80:83]
	v_mfma_f32_16x16x32_bf16 v[76:79], v[202:205], v[182:185], v[76:79]
	v_mfma_f32_16x16x32_bf16 v[72:75], v[210:213], v[182:185], v[72:75]
	v_mfma_f32_16x16x32_bf16 v[68:71], v[202:205], v[194:197], v[68:71]
	v_mfma_f32_16x16x32_bf16 v[64:67], v[210:213], v[194:197], v[64:67]
	v_mfma_f32_16x16x32_bf16 v[92:95], v[206:209], v[170:173], v[92:95]
	v_mfma_f32_16x16x32_bf16 v[88:91], v[214:217], v[170:173], v[88:91]
	v_mfma_f32_16x16x32_bf16 v[84:87], v[206:209], v[178:181], v[84:87]
	v_mfma_f32_16x16x32_bf16 v[80:83], v[214:217], v[178:181], v[80:83]
	v_mfma_f32_16x16x32_bf16 v[76:79], v[206:209], v[186:189], v[76:79]
	v_mfma_f32_16x16x32_bf16 v[72:75], v[214:217], v[186:189], v[72:75]
	v_mfma_f32_16x16x32_bf16 v[68:71], v[206:209], v[198:201], v[68:71]
	v_mfma_f32_16x16x32_bf16 v[64:67], v[214:217], v[198:201], v[64:67]
	s_setprio 0
	s_mov_b32 m0, s40
	v_lshl_add_u64 v[220:221], s[38:39], 0, v[130:131]
	s_barrier
	ds_read_b128 v[166:169], v149 offset:16384
	ds_read_b128 v[170:173], v149 offset:17408
	ds_read_b128 v[174:177], v149 offset:18432
	ds_read_b128 v[178:181], v149 offset:19456
	ds_read_b128 v[182:185], v149 offset:20480
	ds_read_b128 v[186:189], v149 offset:21504
	ds_read_b128 v[194:197], v149 offset:22528
	ds_read_b128 v[198:201], v149 offset:23552
	global_load_lds_dwordx4 v[220:221], off
	v_lshl_add_u64 v[222:223], s[38:39], 0, v[128:129]
	s_mov_b32 m0, s41
	s_nop 0
	global_load_lds_dwordx4 v[222:223], off
	s_barrier
	s_waitcnt lgkmcnt(0)
	s_setprio 1
	s_waitcnt lgkmcnt(0)
	v_mfma_f32_16x16x32_bf16 v[60:63], v[150:153], v[166:169], v[60:63]
	v_mfma_f32_16x16x32_bf16 v[56:59], v[158:161], v[166:169], v[56:59]
	v_mfma_f32_16x16x32_bf16 v[52:55], v[150:153], v[174:177], v[52:55]
	v_mfma_f32_16x16x32_bf16 v[48:51], v[158:161], v[174:177], v[48:51]
	v_mfma_f32_16x16x32_bf16 v[44:47], v[150:153], v[182:185], v[44:47]
	v_mfma_f32_16x16x32_bf16 v[40:43], v[158:161], v[182:185], v[40:43]
	v_mfma_f32_16x16x32_bf16 v[36:39], v[150:153], v[194:197], v[36:39]
	v_mfma_f32_16x16x32_bf16 v[32:35], v[158:161], v[194:197], v[32:35]
	v_mfma_f32_16x16x32_bf16 v[60:63], v[154:157], v[170:173], v[60:63]
	v_mfma_f32_16x16x32_bf16 v[56:59], v[162:165], v[170:173], v[56:59]
	v_mfma_f32_16x16x32_bf16 v[52:55], v[154:157], v[178:181], v[52:55]
	v_mfma_f32_16x16x32_bf16 v[48:51], v[162:165], v[178:181], v[48:51]
	v_mfma_f32_16x16x32_bf16 v[44:47], v[154:157], v[186:189], v[44:47]
	v_mfma_f32_16x16x32_bf16 v[40:43], v[162:165], v[186:189], v[40:43]
	v_mfma_f32_16x16x32_bf16 v[36:39], v[154:157], v[198:201], v[36:39]
	v_mfma_f32_16x16x32_bf16 v[32:35], v[162:165], v[198:201], v[32:35]
	s_setprio 0
	s_barrier
; #define PG8_STAGE(bufoff, gbase, voff) do { _Pragma("unroll") for (int _i = 0; _i < 2; ++_i) \
;         __builtin_amdgcn_global_load_lds((const unsigned*)((const char*)(gbase) + (voff)[_i]), (LAS unsigned*)(lds + (bufoff) + ldsw + _i * 8192), 16, 0, 0); } while (0)
; #define PG8_LDA(dst, b, h) do { _Pragma("unroll") for (int m = 0; m < 4; ++m) _Pragma("unroll") for (int k = 0; k < 2; ++k) dst[m][k] = *(const LAS bf16x8*)(lds + PG8_SA(b, h) + aoff + m * 2048 + k * 1024); } while (0)
; #define PG8_LDB(dst, b, h) do { _Pragma("unroll") for (int n = 0; n < 2; ++n) _Pragma("unroll") for (int k = 0; k < 2; ++k) dst[n][k] = *(const LAS bf16x8*)(lds + PG8_SB(b, h) + boff + n * 2048 + k * 1024); } while (0)
; #define PG8_MMA(ai, bj, At, Bt) do { __builtin_amdgcn_s_setprio(1); _Pragma("unroll") for (int m = 0; m < 4; ++m) _Pragma("unroll") for (int n = 0; n < 2; ++n) _Pragma("unroll") for (int k = 0; k < 2; ++k) \
;         acc[ai][bj][m][n] = __builtin_amdgcn_mfma_f32_16x16x32_bf16(Bt[n][k], At[m][k], acc[ai][bj][m][n], 0, 0, 0); __builtin_amdgcn_s_setprio(0); } while (0)
; #define PG8_WAIT_V(n) asm volatile("s_waitcnt vmcnt(" #n ")" ::: "memory")
; #define PG8_WAIT_L(n) asm volatile("s_waitcnt lgkmcnt(" #n ")" ::: "memory")
; #define PG8_BAR __builtin_amdgcn_s_barrier()
; #define PG8_SCHED __builtin_amdgcn_sched_barrier(0)
; template <class Epi>
; __device__ __forceinline__ void gemm_phase(LAS unsigned char* lds, const Gemm g, const Sched& S, const Epi& E) {
;     ...
;             PG8_STAGE(PG8_SB(0, 1), b2 + hstepB, voffB);
;             PG8_WAIT_V(6); PG8_BAR; PG8_MMA(1, 1, At, B1); PG8_BAR;
;             PG8_LDB(B0, 1, 0); PG8_SCHED; PG8_LDA(At, 1, 0); PG8_STAGE(PG8_SA(0, 1), a2 + hstepA, voffA);
;             PG8_WAIT_L(8); PG8_BAR; PG8_WAIT_L(0); PG8_MMA(0, 0, At, B0); PG8_BAR; PG8_SCHED;
;             PG8_LDB(B1, 1, 1); PG8_STAGE(PG8_SB(1, 0), b3, voffB);
;             PG8_BAR; PG8_WAIT_L(0); PG8_MMA(0, 1, At, B1); PG8_BAR;
;             PG8_LDA(At, 1, 1); PG8_STAGE(PG8_SA(1, 0), a3, voffA);
	s_add_u32 s70, s36, 0x80000
	s_addc_u32 s71, s37, 0
	s_add_i32 s72, s55, s34
	v_lshl_add_u64 v[150:151], s[70:71], 0, v[130:131]
	s_mov_b32 m0, s72
	s_nop 0
	global_load_lds_dwordx4 v[150:151], off
	v_lshl_add_u64 v[150:151], s[70:71], 0, v[128:129]
	s_add_i32 m0, s72, 0x2000
	s_nop 0
	global_load_lds_dwordx4 v[150:151], off
	s_waitcnt vmcnt(6)
	s_barrier
	s_setprio 1
	v_mfma_f32_16x16x32_bf16 v[28:31], v[202:205], v[166:169], v[28:31]
	v_mfma_f32_16x16x32_bf16 v[24:27], v[210:213], v[166:169], v[24:27]
	v_mfma_f32_16x16x32_bf16 v[20:23], v[202:205], v[174:177], v[20:23]
	v_mfma_f32_16x16x32_bf16 v[16:19], v[210:213], v[174:177], v[16:19]
	v_mfma_f32_16x16x32_bf16 v[12:15], v[202:205], v[182:185], v[12:15]
	v_mfma_f32_16x16x32_bf16 v[8:11], v[210:213], v[182:185], v[8:11]
	v_mfma_f32_16x16x32_bf16 v[4:7], v[202:205], v[194:197], v[4:7]
	v_mfma_f32_16x16x32_bf16 v[0:3], v[210:213], v[194:197], v[0:3]
	v_mfma_f32_16x16x32_bf16 v[28:31], v[206:209], v[170:173], v[28:31]
	v_mfma_f32_16x16x32_bf16 v[24:27], v[214:217], v[170:173], v[24:27]
	v_mfma_f32_16x16x32_bf16 v[20:23], v[206:209], v[178:181], v[20:23]
	v_mfma_f32_16x16x32_bf16 v[16:19], v[214:217], v[178:181], v[16:19]
	v_mfma_f32_16x16x32_bf16 v[12:15], v[206:209], v[186:189], v[12:15]
	v_mfma_f32_16x16x32_bf16 v[8:11], v[214:217], v[186:189], v[8:11]
	v_mfma_f32_16x16x32_bf16 v[4:7], v[206:209], v[198:201], v[4:7]
	v_mfma_f32_16x16x32_bf16 v[0:3], v[214:217], v[198:201], v[0:3]
	s_setprio 0
	s_add_i32 s70, 0, 0x18000
	v_add_u32_e32 v162, s70, v148
	s_barrier
	ds_read_b128 v[150:153], v162
	ds_read_b128 v[154:157], v162 offset:1024
	ds_read_b128 v[158:161], v162 offset:2048
	ds_read_b128 v[162:165], v162 offset:3072
	s_add_u32 s38, s38, 0x80000
	s_addc_u32 s39, s39, 0
	s_mov_b32 m0, s43
	v_lshl_add_u64 v[202:203], s[38:39], 0, v[130:131]
	ds_read_b128 v[166:169], v149 offset:32768
	ds_read_b128 v[170:173], v149 offset:33792
	ds_read_b128 v[174:177], v149 offset:34816
	ds_read_b128 v[178:181], v149 offset:35840
	ds_read_b128 v[182:185], v149 offset:36864
	ds_read_b128 v[186:189], v149 offset:37888
	ds_read_b128 v[194:197], v149 offset:38912
	ds_read_b128 v[198:201], v149 offset:39936
	global_load_lds_dwordx4 v[202:203], off
	v_lshl_add_u64 v[202:203], s[38:39], 0, v[128:129]
	s_mov_b32 m0, s46
	s_nop 0
	global_load_lds_dwordx4 v[202:203], off
	s_waitcnt lgkmcnt(8)
	s_barrier
	s_waitcnt lgkmcnt(0)
	s_setprio 1
	s_waitcnt lgkmcnt(0)
	v_mfma_f32_16x16x32_bf16 v[124:127], v[150:153], v[166:169], v[124:127]
	v_mfma_f32_16x16x32_bf16 v[120:123], v[158:161], v[166:169], v[120:123]
	v_mfma_f32_16x16x32_bf16 v[116:119], v[150:153], v[174:177], v[116:119]
	v_mfma_f32_16x16x32_bf16 v[112:115], v[158:161], v[174:177], v[112:115]
	v_mfma_f32_16x16x32_bf16 v[108:111], v[150:153], v[182:185], v[108:111]
	v_mfma_f32_16x16x32_bf16 v[104:107], v[158:161], v[182:185], v[104:107]
	v_mfma_f32_16x16x32_bf16 v[100:103], v[150:153], v[194:197], v[100:103]
	v_mfma_f32_16x16x32_bf16 v[96:99], v[158:161], v[194:197], v[96:99]
	v_mfma_f32_16x16x32_bf16 v[124:127], v[154:157], v[170:173], v[124:127]
	v_mfma_f32_16x16x32_bf16 v[120:123], v[162:165], v[170:173], v[120:123]
	v_mfma_f32_16x16x32_bf16 v[116:119], v[154:157], v[178:181], v[116:119]
	v_mfma_f32_16x16x32_bf16 v[112:115], v[162:165], v[178:181], v[112:115]
	v_mfma_f32_16x16x32_bf16 v[108:111], v[154:157], v[186:189], v[108:111]
	v_mfma_f32_16x16x32_bf16 v[104:107], v[162:165], v[186:189], v[104:107]
	v_mfma_f32_16x16x32_bf16 v[100:103], v[154:157], v[198:201], v[100:103]
	v_mfma_f32_16x16x32_bf16 v[96:99], v[162:165], v[198:201], v[96:99]
	s_setprio 0
	s_barrier
	s_add_i32 s38, 0, 0x1c000
	s_add_i32 s39, s70, s34
	v_add_u32_e32 v214, s38, v148
	v_lshl_add_u64 v[190:191], v[190:191], 0, s[14:15]
	s_mov_b32 m0, s39
	ds_read_b128 v[202:205], v214
	ds_read_b128 v[206:209], v214 offset:1024
	ds_read_b128 v[210:213], v214 offset:2048
	ds_read_b128 v[214:217], v214 offset:3072
	global_load_lds_dwordx4 v[190:191], off
	v_lshl_add_u64 v[190:191], v[218:219], 0, s[14:15]
	s_add_i32 m0, s39, 0x2000
	s_nop 0
	global_load_lds_dwordx4 v[190:191], off
	s_barrier
	s_waitcnt lgkmcnt(0)
	s_setprio 1
	s_waitcnt lgkmcnt(0)
	v_mfma_f32_16x16x32_bf16 v[92:95], v[202:205], v[166:169], v[92:95]
	v_mfma_f32_16x16x32_bf16 v[88:91], v[210:213], v[166:169], v[88:91]
	v_mfma_f32_16x16x32_bf16 v[84:87], v[202:205], v[174:177], v[84:87]
	v_mfma_f32_16x16x32_bf16 v[80:83], v[210:213], v[174:177], v[80:83]
	v_mfma_f32_16x16x32_bf16 v[76:79], v[202:205], v[182:185], v[76:79]
	v_mfma_f32_16x16x32_bf16 v[72:75], v[210:213], v[182:185], v[72:75]
	v_mfma_f32_16x16x32_bf16 v[68:71], v[202:205], v[194:197], v[68:71]
	v_mfma_f32_16x16x32_bf16 v[64:67], v[210:213], v[194:197], v[64:67]
	v_mfma_f32_16x16x32_bf16 v[92:95], v[206:209], v[170:173], v[92:95]
	v_mfma_f32_16x16x32_bf16 v[88:91], v[214:217], v[170:173], v[88:91]
	v_mfma_f32_16x16x32_bf16 v[84:87], v[206:209], v[178:181], v[84:87]
	v_mfma_f32_16x16x32_bf16 v[80:83], v[214:217], v[178:181], v[80:83]
	v_mfma_f32_16x16x32_bf16 v[76:79], v[206:209], v[186:189], v[76:79]
	v_mfma_f32_16x16x32_bf16 v[72:75], v[214:217], v[186:189], v[72:75]
	v_mfma_f32_16x16x32_bf16 v[68:71], v[206:209], v[198:201], v[68:71]
	v_mfma_f32_16x16x32_bf16 v[64:67], v[214:217], v[198:201], v[64:67]
	s_setprio 0
	s_mov_b32 m0, s52
	v_lshl_add_u64 v[190:191], v[220:221], 0, s[14:15]
	s_barrier
	ds_read_b128 v[166:169], v149 offset:49152
	ds_read_b128 v[170:173], v149 offset:50176
	ds_read_b128 v[174:177], v149 offset:51200
	ds_read_b128 v[178:181], v149 offset:52224
	ds_read_b128 v[182:185], v149 offset:53248
	ds_read_b128 v[186:189], v149 offset:54272
	ds_read_b128 v[194:197], v149 offset:55296
	ds_read_b128 v[198:201], v149 offset:56320
	global_load_lds_dwordx4 v[190:191], off
	v_lshl_add_u64 v[190:191], v[222:223], 0, s[14:15]
	s_mov_b32 m0, s53
	s_nop 0
	global_load_lds_dwordx4 v[190:191], off
	s_barrier
; __device__ __forceinline__ unsigned cvt_pk_bf16(float lo, float hi) { unsigned r; asm volatile("v_cvt_pk_bf16_f32 %0, %1, %2" : "=v"(r) : "v"(lo), "v"(hi)); return r; }
; #define PG8_STAGE(bufoff, gbase, voff) do { _Pragma("unroll") for (int _i = 0; _i < 2; ++_i) \
;         __builtin_amdgcn_global_load_lds((const unsigned*)((const char*)(gbase) + (voff)[_i]), (LAS unsigned*)(lds + (bufoff) + ldsw + _i * 8192), 16, 0, 0); } while (0)
; #define PG8_MMA(ai, bj, At, Bt) do { __builtin_amdgcn_s_setprio(1); _Pragma("unroll") for (int m = 0; m < 4; ++m) _Pragma("unroll") for (int n = 0; n < 2; ++n) _Pragma("unroll") for (int k = 0; k < 2; ++k) \
;         acc[ai][bj][m][n] = __builtin_amdgcn_mfma_f32_16x16x32_bf16(Bt[n][k], At[m][k], acc[ai][bj][m][n], 0, 0, 0); __builtin_amdgcn_s_setprio(0); } while (0)
; #define PG8_WAIT_V(n) asm volatile("s_waitcnt vmcnt(" #n ")" ::: "memory")
; #define PG8_WAIT_L(n) asm volatile("s_waitcnt lgkmcnt(" #n ")" ::: "memory")
; #define PG8_BAR __builtin_amdgcn_s_barrier()
; #define PG8_SCHED __builtin_amdgcn_sched_barrier(0)
; template <class Epi>
; __device__ __forceinline__ void gemm_phase(LAS unsigned char* lds, const Gemm g, const Sched& S, const Epi& E) {
;     ...
;             PG8_BAR; PG8_WAIT_L(0); PG8_MMA(1, 0, At, B0); PG8_BAR; PG8_SCHED;
;             PG8_STAGE(PG8_SB(1, 1), b3 + hstepB, voffB);
;             PG8_WAIT_V(6); PG8_BAR; PG8_MMA(1, 1, At, B1); PG8_BAR;
;     __device__ __forceinline__ void operator()(AccRef acc, const Unit& u, int wr, int wc, int fr, int fq) const {
;     ...
;             for (int m = 0; m < 4; ++m) { const size_t row = (size_t)u.pm * 256 + ai * 128 + wr * 64 + m * 16 + fr; float o[8];
; #pragma unroll
;                 for (int bj = 0; bj < 2; ++bj) { const f32x4 gg = acc[ai][bj][m][0], uu = acc[ai][bj][m][1];
; #pragma unroll
;                     for (int j = 0; j < 4; ++j) o[4 * bj + j] = gg[j] * __builtin_amdgcn_rcpf(1.0f + __expf(-gg[j])) * uu[j]; }
;                 u32x4 w; w.x = cvt_pk_bf16(o[0], o[1]); w.y = cvt_pk_bf16(o[2], o[3]); w.z = cvt_pk_bf16(o[4], o[5]); w.w = cvt_pk_bf16(o[6], o[7]);
;                 *(u32x4*)(act + row * FF_ + (u.pn * 4 + wc) * 32 + 8 * fq) = w; }
	s_waitcnt lgkmcnt(0)
	s_setprio 1
	s_waitcnt lgkmcnt(0)
	v_mfma_f32_16x16x32_bf16 v[60:63], v[150:153], v[166:169], v[60:63]
	v_mfma_f32_16x16x32_bf16 v[56:59], v[158:161], v[166:169], v[56:59]
	v_mfma_f32_16x16x32_bf16 v[52:55], v[150:153], v[174:177], v[52:55]
	v_mfma_f32_16x16x32_bf16 v[48:51], v[158:161], v[174:177], v[48:51]
	v_mfma_f32_16x16x32_bf16 v[44:47], v[150:153], v[182:185], v[44:47]
	v_mfma_f32_16x16x32_bf16 v[40:43], v[158:161], v[182:185], v[40:43]
	v_mfma_f32_16x16x32_bf16 v[36:39], v[150:153], v[194:197], v[36:39]
	v_mfma_f32_16x16x32_bf16 v[32:35], v[158:161], v[194:197], v[32:35]
	v_mfma_f32_16x16x32_bf16 v[60:63], v[154:157], v[170:173], v[60:63]
	v_mfma_f32_16x16x32_bf16 v[56:59], v[162:165], v[170:173], v[56:59]
	v_mfma_f32_16x16x32_bf16 v[52:55], v[154:157], v[178:181], v[52:55]
	v_mfma_f32_16x16x32_bf16 v[48:51], v[162:165], v[178:181], v[48:51]
	v_mfma_f32_16x16x32_bf16 v[44:47], v[154:157], v[186:189], v[44:47]
	v_mfma_f32_16x16x32_bf16 v[40:43], v[162:165], v[186:189], v[40:43]
	v_mfma_f32_16x16x32_bf16 v[36:39], v[154:157], v[198:201], v[36:39]
	v_mfma_f32_16x16x32_bf16 v[32:35], v[162:165], v[198:201], v[32:35]
	s_setprio 0
	s_barrier
	s_add_u32 s36, s36, 0x80080
	s_addc_u32 s37, s37, 0
	s_add_i32 s38, s38, s34
	v_lshl_add_u64 v[150:151], s[36:37], 0, v[130:131]
	s_mov_b32 m0, s38
	s_nop 0
	global_load_lds_dwordx4 v[150:151], off
	v_lshl_add_u64 v[150:151], s[36:37], 0, v[128:129]
	s_add_i32 m0, s38, 0x2000
	s_nop 0
	global_load_lds_dwordx4 v[150:151], off
	s_waitcnt vmcnt(6)
	s_barrier
	s_setprio 1
	v_mfma_f32_16x16x32_bf16 v[28:31], v[202:205], v[166:169], v[28:31]
	v_mfma_f32_16x16x32_bf16 v[24:27], v[210:213], v[166:169], v[24:27]
	v_mfma_f32_16x16x32_bf16 v[20:23], v[202:205], v[174:177], v[20:23]
	v_mfma_f32_16x16x32_bf16 v[16:19], v[210:213], v[174:177], v[16:19]
	v_mfma_f32_16x16x32_bf16 v[12:15], v[202:205], v[182:185], v[12:15]
	v_mfma_f32_16x16x32_bf16 v[8:11], v[210:213], v[182:185], v[8:11]
	v_mfma_f32_16x16x32_bf16 v[4:7], v[202:205], v[194:197], v[4:7]
	v_mfma_f32_16x16x32_bf16 v[0:3], v[210:213], v[194:197], v[0:3]
	v_mfma_f32_16x16x32_bf16 v[28:31], v[206:209], v[170:173], v[28:31]
	v_mfma_f32_16x16x32_bf16 v[24:27], v[214:217], v[170:173], v[24:27]
	v_mfma_f32_16x16x32_bf16 v[20:23], v[206:209], v[178:181], v[20:23]
	v_mfma_f32_16x16x32_bf16 v[16:19], v[214:217], v[178:181], v[16:19]
	v_mfma_f32_16x16x32_bf16 v[12:15], v[206:209], v[186:189], v[12:15]
	v_mfma_f32_16x16x32_bf16 v[8:11], v[214:217], v[186:189], v[8:11]
	v_mfma_f32_16x16x32_bf16 v[4:7], v[206:209], v[198:201], v[4:7]
	v_mfma_f32_16x16x32_bf16 v[0:3], v[214:217], v[198:201], v[0:3]
	s_setprio 0
	s_add_i32 s67, s67, 2
	s_add_u32 s24, s24, 0x100
	s_addc_u32 s25, s25, 0
	s_cmp_gt_u32 s67, 29
	s_barrier
	s_cbranch_scc0 .LBB0_3085
	v_mov_b32_e32 v170, 0xbfb8aa3b
	v_mov_b32_e32 v172, 1.0
	v_mov_b64_e32 v[176:177], 0
	v_mov_b64_e32 v[178:179], 0
	s_add_u32 s24, s11, 0xffffff00
	s_addc_u32 s25, s64, -1
	s_ashr_i32 s11, s10, 31
	s_lshl_b64 s[36:37], s[10:11], 8
	v_lshl_add_u64 v[144:145], v[134:135], 0, s[36:37]
	v_mov_b64_e32 v[146:147], s[44:45]
	v_mad_u64_u32 v[146:147], s[38:39], v144, s56, v[146:147]
	s_lshl_b32 s11, s50, 7
	v_mov_b32_e32 v144, v147
	s_or_b32 s36, s11, s51
	v_mad_u64_u32 v[144:145], s[38:39], v145, s56, v[144:145]
	s_ashr_i32 s37, s36, 31
	v_mov_b32_e32 v147, v144
	v_lshl_add_u64 v[144:145], s[36:37], 1, v[146:147]
	v_lshl_add_u64 v[144:145], v[144:145], 0, v[132:133]
	v_pk_mul_f32 v[162:163], v[124:125], v[170:171] op_sel_hi:[1,0]
	v_pk_mul_f32 v[164:165], v[126:127], v[170:171] op_sel_hi:[1,0]
	v_pk_mul_f32 v[166:167], v[92:93], v[170:171] op_sel_hi:[1,0]
	v_pk_mul_f32 v[168:169], v[94:95], v[170:171] op_sel_hi:[1,0]
	v_exp_f32_e32 v162, v162
	v_exp_f32_e32 v163, v163
	v_exp_f32_e32 v164, v164
	v_exp_f32_e32 v165, v165
	v_exp_f32_e32 v166, v166
	v_exp_f32_e32 v167, v167
	v_exp_f32_e32 v168, v168
	v_exp_f32_e32 v169, v169
	v_pk_add_f32 v[162:163], v[162:163], v[172:173] op_sel_hi:[1,0]
	v_pk_add_f32 v[164:165], v[164:165], v[172:173] op_sel_hi:[1,0]
	v_pk_add_f32 v[166:167], v[166:167], v[172:173] op_sel_hi:[1,0]
	v_pk_add_f32 v[168:169], v[168:169], v[172:173] op_sel_hi:[1,0]
	v_rcp_f32_e32 v162, v162
	v_rcp_f32_e32 v163, v163
	v_rcp_f32_e32 v164, v164
	v_rcp_f32_e32 v165, v165
	v_rcp_f32_e32 v166, v166
	v_rcp_f32_e32 v167, v167
	v_rcp_f32_e32 v168, v168
	v_rcp_f32_e32 v169, v169
	v_pk_mul_f32 v[162:163], v[124:125], v[162:163]
	v_pk_mul_f32 v[164:165], v[126:127], v[164:165]
	v_pk_mul_f32 v[166:167], v[92:93], v[166:167]
	v_pk_mul_f32 v[168:169], v[94:95], v[168:169]
	v_pk_mul_f32 v[162:163], v[120:121], v[162:163]
	v_pk_mul_f32 v[164:165], v[122:123], v[164:165]
	v_pk_mul_f32 v[166:167], v[88:89], v[166:167]
	v_pk_mul_f32 v[168:169], v[90:91], v[168:169]
	v_cvt_pk_bf16_f32 v150, v162, v163
	v_cvt_pk_bf16_f32 v151, v164, v165
	v_cvt_pk_bf16_f32 v152, v166, v167
	v_cvt_pk_bf16_f32 v153, v168, v169
	global_store_dwordx4 v[144:145], v[150:153], off nt
	v_add_co_u32_e32 v146, vcc, s57, v144
	s_nop 0
	v_addc_co_u32_e32 v147, vcc, 0, v145, vcc
	v_pk_mul_f32 v[162:163], v[116:117], v[170:171] op_sel_hi:[1,0]
	v_pk_mul_f32 v[164:165], v[118:119], v[170:171] op_sel_hi:[1,0]
	v_pk_mul_f32 v[166:167], v[84:85], v[170:171] op_sel_hi:[1,0]
	v_pk_mul_f32 v[168:169], v[86:87], v[170:171] op_sel_hi:[1,0]
	v_exp_f32_e32 v162, v162
	v_exp_f32_e32 v163, v163
	v_exp_f32_e32 v164, v164
	v_exp_f32_e32 v165, v165
	v_exp_f32_e32 v166, v166
	v_exp_f32_e32 v167, v167
	v_exp_f32_e32 v168, v168
	v_exp_f32_e32 v169, v169
	v_pk_add_f32 v[162:163], v[162:163], v[172:173] op_sel_hi:[1,0]
	v_pk_add_f32 v[164:165], v[164:165], v[172:173] op_sel_hi:[1,0]
; __device__ __forceinline__ unsigned cvt_pk_bf16(float lo, float hi) { unsigned r; asm volatile("v_cvt_pk_bf16_f32 %0, %1, %2" : "=v"(r) : "v"(lo), "v"(hi)); return r; }
; template <class Epi>
; __device__ __forceinline__ void gemm_phase(LAS unsigned char* lds, const Gemm g, const Sched& S, const Epi& E) {
;     ...
; #pragma unroll
;         for (int a = 0; a < 2; ++a)
; #pragma unroll
;             for (int b = 0; b < 2; ++b)
; #pragma unroll
;                 for (int m = 0; m < 4; ++m)
; #pragma unroll
;                     for (int n = 0; n < 2; ++n) acc[a][b][m][n] = (f32x4){0.f, 0.f, 0.f, 0.f};
;     __device__ __forceinline__ void operator()(AccRef acc, const Unit& u, int wr, int wc, int fr, int fq) const {
;     ...
;         for (int ai = 0; ai < 2; ++ai)
; #pragma unroll
;             for (int m = 0; m < 4; ++m) { const size_t row = (size_t)u.pm * 256 + ai * 128 + wr * 64 + m * 16 + fr; float o[8];
; #pragma unroll
;                 for (int bj = 0; bj < 2; ++bj) { const f32x4 gg = acc[ai][bj][m][0], uu = acc[ai][bj][m][1];
; #pragma unroll
;                     for (int j = 0; j < 4; ++j) o[4 * bj + j] = gg[j] * __builtin_amdgcn_rcpf(1.0f + __expf(-gg[j])) * uu[j]; }
;                 u32x4 w; w.x = cvt_pk_bf16(o[0], o[1]); w.y = cvt_pk_bf16(o[2], o[3]); w.z = cvt_pk_bf16(o[4], o[5]); w.w = cvt_pk_bf16(o[6], o[7]);
;                 *(u32x4*)(act + row * FF_ + (u.pn * 4 + wc) * 32 + 8 * fq) = w; }
	v_pk_add_f32 v[166:167], v[166:167], v[172:173] op_sel_hi:[1,0]
	v_pk_add_f32 v[168:169], v[168:169], v[172:173] op_sel_hi:[1,0]
	v_rcp_f32_e32 v162, v162
	v_rcp_f32_e32 v163, v163
	v_rcp_f32_e32 v164, v164
	v_rcp_f32_e32 v165, v165
	v_rcp_f32_e32 v166, v166
	v_rcp_f32_e32 v167, v167
	v_rcp_f32_e32 v168, v168
	v_rcp_f32_e32 v169, v169
	v_pk_mul_f32 v[162:163], v[116:117], v[162:163]
	v_pk_mul_f32 v[164:165], v[118:119], v[164:165]
	v_pk_mul_f32 v[166:167], v[84:85], v[166:167]
	v_pk_mul_f32 v[168:169], v[86:87], v[168:169]
	v_pk_mul_f32 v[162:163], v[112:113], v[162:163]
	v_pk_mul_f32 v[164:165], v[114:115], v[164:165]
	v_pk_mul_f32 v[166:167], v[80:81], v[166:167]
	v_pk_mul_f32 v[168:169], v[82:83], v[168:169]
	v_cvt_pk_bf16_f32 v150, v162, v163
	v_cvt_pk_bf16_f32 v151, v164, v165
	v_cvt_pk_bf16_f32 v152, v166, v167
	v_cvt_pk_bf16_f32 v153, v168, v169
	global_store_dwordx4 v[146:147], v[150:153], off nt
	v_mfma_f32_32x32x16_bf16 v[80:95], v[176:179], v[176:179], 0
	v_mfma_f32_32x32x16_bf16 v[112:127], v[176:179], v[176:179], 0
	v_add_co_u32_e32 v146, vcc, s58, v144
	s_nop 0
	v_addc_co_u32_e32 v147, vcc, 0, v145, vcc
	v_pk_mul_f32 v[162:163], v[108:109], v[170:171] op_sel_hi:[1,0]
	v_pk_mul_f32 v[164:165], v[110:111], v[170:171] op_sel_hi:[1,0]
	v_pk_mul_f32 v[166:167], v[76:77], v[170:171] op_sel_hi:[1,0]
	v_pk_mul_f32 v[168:169], v[78:79], v[170:171] op_sel_hi:[1,0]
	v_exp_f32_e32 v162, v162
	v_exp_f32_e32 v163, v163
	v_exp_f32_e32 v164, v164
	v_exp_f32_e32 v165, v165
	v_exp_f32_e32 v166, v166
	v_exp_f32_e32 v167, v167
	v_exp_f32_e32 v168, v168
	v_exp_f32_e32 v169, v169
	v_pk_add_f32 v[162:163], v[162:163], v[172:173] op_sel_hi:[1,0]
	v_pk_add_f32 v[164:165], v[164:165], v[172:173] op_sel_hi:[1,0]
	v_pk_add_f32 v[166:167], v[166:167], v[172:173] op_sel_hi:[1,0]
	v_pk_add_f32 v[168:169], v[168:169], v[172:173] op_sel_hi:[1,0]
	v_rcp_f32_e32 v162, v162
	v_rcp_f32_e32 v163, v163
	v_rcp_f32_e32 v164, v164
	v_rcp_f32_e32 v165, v165
	v_rcp_f32_e32 v166, v166
	v_rcp_f32_e32 v167, v167
	v_rcp_f32_e32 v168, v168
	v_rcp_f32_e32 v169, v169
	v_pk_mul_f32 v[162:163], v[108:109], v[162:163]
	v_pk_mul_f32 v[164:165], v[110:111], v[164:165]
	v_pk_mul_f32 v[166:167], v[76:77], v[166:167]
	v_pk_mul_f32 v[168:169], v[78:79], v[168:169]
	v_pk_mul_f32 v[162:163], v[104:105], v[162:163]
	v_pk_mul_f32 v[164:165], v[106:107], v[164:165]
	v_pk_mul_f32 v[166:167], v[72:73], v[166:167]
	v_pk_mul_f32 v[168:169], v[74:75], v[168:169]
	v_cvt_pk_bf16_f32 v150, v162, v163
	v_cvt_pk_bf16_f32 v151, v164, v165
	v_cvt_pk_bf16_f32 v152, v166, v167
	v_cvt_pk_bf16_f32 v153, v168, v169
	global_store_dwordx4 v[146:147], v[150:153], off nt
	v_add_co_u32_e32 v146, vcc, s59, v144
	s_nop 0
	v_addc_co_u32_e32 v147, vcc, 0, v145, vcc
	v_pk_mul_f32 v[162:163], v[100:101], v[170:171] op_sel_hi:[1,0]
	v_pk_mul_f32 v[164:165], v[102:103], v[170:171] op_sel_hi:[1,0]
	v_pk_mul_f32 v[166:167], v[68:69], v[170:171] op_sel_hi:[1,0]
	v_pk_mul_f32 v[168:169], v[70:71], v[170:171] op_sel_hi:[1,0]
	v_exp_f32_e32 v162, v162
	v_exp_f32_e32 v163, v163
	v_exp_f32_e32 v164, v164
	v_exp_f32_e32 v165, v165
	v_exp_f32_e32 v166, v166
	v_exp_f32_e32 v167, v167
	v_exp_f32_e32 v168, v168
	v_exp_f32_e32 v169, v169
	v_pk_add_f32 v[162:163], v[162:163], v[172:173] op_sel_hi:[1,0]
	v_pk_add_f32 v[164:165], v[164:165], v[172:173] op_sel_hi:[1,0]
	v_pk_add_f32 v[166:167], v[166:167], v[172:173] op_sel_hi:[1,0]
	v_pk_add_f32 v[168:169], v[168:169], v[172:173] op_sel_hi:[1,0]
	v_rcp_f32_e32 v162, v162
	v_rcp_f32_e32 v163, v163
	v_rcp_f32_e32 v164, v164
	v_rcp_f32_e32 v165, v165
	v_rcp_f32_e32 v166, v166
	v_rcp_f32_e32 v167, v167
	v_rcp_f32_e32 v168, v168
	v_rcp_f32_e32 v169, v169
	v_pk_mul_f32 v[162:163], v[100:101], v[162:163]
	v_pk_mul_f32 v[164:165], v[102:103], v[164:165]
	v_pk_mul_f32 v[166:167], v[68:69], v[166:167]
	v_pk_mul_f32 v[168:169], v[70:71], v[168:169]
	v_pk_mul_f32 v[162:163], v[96:97], v[162:163]
	v_pk_mul_f32 v[164:165], v[98:99], v[164:165]
	v_pk_mul_f32 v[166:167], v[64:65], v[166:167]
	v_pk_mul_f32 v[168:169], v[66:67], v[168:169]
	v_cvt_pk_bf16_f32 v150, v162, v163
	v_cvt_pk_bf16_f32 v151, v164, v165
	v_cvt_pk_bf16_f32 v152, v166, v167
	v_cvt_pk_bf16_f32 v153, v168, v169
	global_store_dwordx4 v[146:147], v[150:153], off nt
	v_mfma_f32_32x32x16_bf16 v[64:79], v[176:179], v[176:179], 0
	v_mfma_f32_32x32x16_bf16 v[96:111], v[176:179], v[176:179], 0
	v_add_co_u32_e32 v146, vcc, s60, v144
	s_nop 0
	v_addc_co_u32_e32 v147, vcc, 0, v145, vcc
	v_pk_mul_f32 v[162:163], v[60:61], v[170:171] op_sel_hi:[1,0]
	v_pk_mul_f32 v[164:165], v[62:63], v[170:171] op_sel_hi:[1,0]
	v_pk_mul_f32 v[166:167], v[28:29], v[170:171] op_sel_hi:[1,0]
	v_pk_mul_f32 v[168:169], v[30:31], v[170:171] op_sel_hi:[1,0]
	v_exp_f32_e32 v162, v162
	v_exp_f32_e32 v163, v163
	v_exp_f32_e32 v164, v164
	v_exp_f32_e32 v165, v165
	v_exp_f32_e32 v166, v166
	v_exp_f32_e32 v167, v167
	v_exp_f32_e32 v168, v168
	v_exp_f32_e32 v169, v169
	v_pk_add_f32 v[162:163], v[162:163], v[172:173] op_sel_hi:[1,0]
	v_pk_add_f32 v[164:165], v[164:165], v[172:173] op_sel_hi:[1,0]
	v_pk_add_f32 v[166:167], v[166:167], v[172:173] op_sel_hi:[1,0]
	v_pk_add_f32 v[168:169], v[168:169], v[172:173] op_sel_hi:[1,0]
	v_rcp_f32_e32 v162, v162
	v_rcp_f32_e32 v163, v163
	v_rcp_f32_e32 v164, v164
	v_rcp_f32_e32 v165, v165
	v_rcp_f32_e32 v166, v166
	v_rcp_f32_e32 v167, v167
	v_rcp_f32_e32 v168, v168
	v_rcp_f32_e32 v169, v169
	v_pk_mul_f32 v[162:163], v[60:61], v[162:163]
	v_pk_mul_f32 v[164:165], v[62:63], v[164:165]
	v_pk_mul_f32 v[166:167], v[28:29], v[166:167]
	v_pk_mul_f32 v[168:169], v[30:31], v[168:169]
; __device__ __forceinline__ unsigned cvt_pk_bf16(float lo, float hi) { unsigned r; asm volatile("v_cvt_pk_bf16_f32 %0, %1, %2" : "=v"(r) : "v"(lo), "v"(hi)); return r; }
; template <class Epi>
; __device__ __forceinline__ void gemm_phase(LAS unsigned char* lds, const Gemm g, const Sched& S, const Epi& E) {
;     ...
;         if (!has_next) break;
; #pragma unroll
;         for (int a = 0; a < 2; ++a)
; #pragma unroll
;             for (int b = 0; b < 2; ++b)
; #pragma unroll
;                 for (int m = 0; m < 4; ++m)
; #pragma unroll
;                     for (int n = 0; n < 2; ++n) acc[a][b][m][n] = (f32x4){0.f, 0.f, 0.f, 0.f};
;         cur = nxt; cA = nA; cB = nB; ++ui;
;     __device__ __forceinline__ void operator()(AccRef acc, const Unit& u, int wr, int wc, int fr, int fq) const {
;     ...
;         for (int ai = 0; ai < 2; ++ai)
; #pragma unroll
;             for (int m = 0; m < 4; ++m) { const size_t row = (size_t)u.pm * 256 + ai * 128 + wr * 64 + m * 16 + fr; float o[8];
; #pragma unroll
;                 for (int bj = 0; bj < 2; ++bj) { const f32x4 gg = acc[ai][bj][m][0], uu = acc[ai][bj][m][1];
; #pragma unroll
;                     for (int j = 0; j < 4; ++j) o[4 * bj + j] = gg[j] * __builtin_amdgcn_rcpf(1.0f + __expf(-gg[j])) * uu[j]; }
;                 u32x4 w; w.x = cvt_pk_bf16(o[0], o[1]); w.y = cvt_pk_bf16(o[2], o[3]); w.z = cvt_pk_bf16(o[4], o[5]); w.w = cvt_pk_bf16(o[6], o[7]);
;                 *(u32x4*)(act + row * FF_ + (u.pn * 4 + wc) * 32 + 8 * fq) = w; }
	v_pk_mul_f32 v[162:163], v[56:57], v[162:163]
	v_pk_mul_f32 v[164:165], v[58:59], v[164:165]
	v_pk_mul_f32 v[166:167], v[24:25], v[166:167]
	v_pk_mul_f32 v[168:169], v[26:27], v[168:169]
	v_cvt_pk_bf16_f32 v150, v162, v163
	v_cvt_pk_bf16_f32 v151, v164, v165
	v_cvt_pk_bf16_f32 v152, v166, v167
	v_cvt_pk_bf16_f32 v153, v168, v169
	global_store_dwordx4 v[146:147], v[150:153], off nt
	v_add_co_u32_e32 v146, vcc, s61, v144
	s_nop 0
	v_addc_co_u32_e32 v147, vcc, 0, v145, vcc
	v_pk_mul_f32 v[162:163], v[52:53], v[170:171] op_sel_hi:[1,0]
	v_pk_mul_f32 v[164:165], v[54:55], v[170:171] op_sel_hi:[1,0]
	v_pk_mul_f32 v[166:167], v[20:21], v[170:171] op_sel_hi:[1,0]
	v_pk_mul_f32 v[168:169], v[22:23], v[170:171] op_sel_hi:[1,0]
	v_exp_f32_e32 v162, v162
	v_exp_f32_e32 v163, v163
	v_exp_f32_e32 v164, v164
	v_exp_f32_e32 v165, v165
	v_exp_f32_e32 v166, v166
	v_exp_f32_e32 v167, v167
	v_exp_f32_e32 v168, v168
	v_exp_f32_e32 v169, v169
	v_pk_add_f32 v[162:163], v[162:163], v[172:173] op_sel_hi:[1,0]
	v_pk_add_f32 v[164:165], v[164:165], v[172:173] op_sel_hi:[1,0]
	v_pk_add_f32 v[166:167], v[166:167], v[172:173] op_sel_hi:[1,0]
	v_pk_add_f32 v[168:169], v[168:169], v[172:173] op_sel_hi:[1,0]
	v_rcp_f32_e32 v162, v162
	v_rcp_f32_e32 v163, v163
	v_rcp_f32_e32 v164, v164
	v_rcp_f32_e32 v165, v165
	v_rcp_f32_e32 v166, v166
	v_rcp_f32_e32 v167, v167
	v_rcp_f32_e32 v168, v168
	v_rcp_f32_e32 v169, v169
	v_pk_mul_f32 v[162:163], v[52:53], v[162:163]
	v_pk_mul_f32 v[164:165], v[54:55], v[164:165]
	v_pk_mul_f32 v[166:167], v[20:21], v[166:167]
	v_pk_mul_f32 v[168:169], v[22:23], v[168:169]
	v_pk_mul_f32 v[162:163], v[48:49], v[162:163]
	v_pk_mul_f32 v[164:165], v[50:51], v[164:165]
	v_pk_mul_f32 v[166:167], v[16:17], v[166:167]
	v_pk_mul_f32 v[168:169], v[18:19], v[168:169]
	v_cvt_pk_bf16_f32 v150, v162, v163
	v_cvt_pk_bf16_f32 v151, v164, v165
	v_cvt_pk_bf16_f32 v152, v166, v167
	v_cvt_pk_bf16_f32 v153, v168, v169
	global_store_dwordx4 v[146:147], v[150:153], off nt
	v_mfma_f32_32x32x16_bf16 v[16:31], v[176:179], v[176:179], 0
	v_mfma_f32_32x32x16_bf16 v[48:63], v[176:179], v[176:179], 0
	v_add_co_u32_e32 v146, vcc, s62, v144
	s_nop 0
	v_addc_co_u32_e32 v147, vcc, 0, v145, vcc
	v_pk_mul_f32 v[162:163], v[44:45], v[170:171] op_sel_hi:[1,0]
	v_pk_mul_f32 v[164:165], v[46:47], v[170:171] op_sel_hi:[1,0]
	v_pk_mul_f32 v[166:167], v[12:13], v[170:171] op_sel_hi:[1,0]
	v_pk_mul_f32 v[168:169], v[14:15], v[170:171] op_sel_hi:[1,0]
	v_exp_f32_e32 v162, v162
	v_exp_f32_e32 v163, v163
	v_exp_f32_e32 v164, v164
	v_exp_f32_e32 v165, v165
	v_exp_f32_e32 v166, v166
	v_exp_f32_e32 v167, v167
	v_exp_f32_e32 v168, v168
	v_exp_f32_e32 v169, v169
	v_pk_add_f32 v[162:163], v[162:163], v[172:173] op_sel_hi:[1,0]
	v_pk_add_f32 v[164:165], v[164:165], v[172:173] op_sel_hi:[1,0]
	v_pk_add_f32 v[166:167], v[166:167], v[172:173] op_sel_hi:[1,0]
	v_pk_add_f32 v[168:169], v[168:169], v[172:173] op_sel_hi:[1,0]
	v_rcp_f32_e32 v162, v162
	v_rcp_f32_e32 v163, v163
	v_rcp_f32_e32 v164, v164
	v_rcp_f32_e32 v165, v165
	v_rcp_f32_e32 v166, v166
	v_rcp_f32_e32 v167, v167
	v_rcp_f32_e32 v168, v168
	v_rcp_f32_e32 v169, v169
	v_pk_mul_f32 v[162:163], v[44:45], v[162:163]
	v_pk_mul_f32 v[164:165], v[46:47], v[164:165]
	v_pk_mul_f32 v[166:167], v[12:13], v[166:167]
	v_pk_mul_f32 v[168:169], v[14:15], v[168:169]
	v_pk_mul_f32 v[162:163], v[40:41], v[162:163]
	v_pk_mul_f32 v[164:165], v[42:43], v[164:165]
	v_pk_mul_f32 v[166:167], v[8:9], v[166:167]
	v_pk_mul_f32 v[168:169], v[10:11], v[168:169]
	v_cvt_pk_bf16_f32 v150, v162, v163
	v_cvt_pk_bf16_f32 v151, v164, v165
	v_cvt_pk_bf16_f32 v152, v166, v167
	v_cvt_pk_bf16_f32 v153, v168, v169
	global_store_dwordx4 v[146:147], v[150:153], off nt
	v_add_co_u32_e32 v144, vcc, 0x1e4000, v144
	v_addc_co_u32_e32 v145, vcc, 0, v145, vcc
	s_andn2_b64 vcc, exec, s[8:9]
	v_pk_mul_f32 v[162:163], v[36:37], v[170:171] op_sel_hi:[1,0]
	v_pk_mul_f32 v[164:165], v[38:39], v[170:171] op_sel_hi:[1,0]
	v_pk_mul_f32 v[166:167], v[4:5], v[170:171] op_sel_hi:[1,0]
	v_pk_mul_f32 v[168:169], v[6:7], v[170:171] op_sel_hi:[1,0]
	v_exp_f32_e32 v162, v162
	v_exp_f32_e32 v163, v163
	v_exp_f32_e32 v164, v164
	v_exp_f32_e32 v165, v165
	v_exp_f32_e32 v166, v166
	v_exp_f32_e32 v167, v167
	v_exp_f32_e32 v168, v168
	v_exp_f32_e32 v169, v169
	v_pk_add_f32 v[162:163], v[162:163], v[172:173] op_sel_hi:[1,0]
	v_pk_add_f32 v[164:165], v[164:165], v[172:173] op_sel_hi:[1,0]
	v_pk_add_f32 v[166:167], v[166:167], v[172:173] op_sel_hi:[1,0]
	v_pk_add_f32 v[168:169], v[168:169], v[172:173] op_sel_hi:[1,0]
	v_rcp_f32_e32 v162, v162
	v_rcp_f32_e32 v163, v163
	v_rcp_f32_e32 v164, v164
	v_rcp_f32_e32 v165, v165
	v_rcp_f32_e32 v166, v166
	v_rcp_f32_e32 v167, v167
	v_rcp_f32_e32 v168, v168
	v_rcp_f32_e32 v169, v169
	v_pk_mul_f32 v[162:163], v[36:37], v[162:163]
	v_pk_mul_f32 v[164:165], v[38:39], v[164:165]
	v_pk_mul_f32 v[166:167], v[4:5], v[166:167]
	v_pk_mul_f32 v[168:169], v[6:7], v[168:169]
	v_pk_mul_f32 v[162:163], v[32:33], v[162:163]
	v_pk_mul_f32 v[164:165], v[34:35], v[164:165]
	v_pk_mul_f32 v[166:167], v[0:1], v[166:167]
	v_pk_mul_f32 v[168:169], v[2:3], v[168:169]
	v_cvt_pk_bf16_f32 v150, v162, v163
	v_cvt_pk_bf16_f32 v151, v164, v165
	v_cvt_pk_bf16_f32 v152, v166, v167
	v_cvt_pk_bf16_f32 v153, v168, v169
	global_store_dwordx4 v[144:145], v[150:153], off nt
	v_mfma_f32_32x32x16_bf16 v[0:15], v[176:179], v[176:179], 0
	v_mfma_f32_32x32x16_bf16 v[32:47], v[176:179], v[176:179], 0
	s_cbranch_vccz .LBB0_3081
	s_mov_b64 s[20:21], s[24:25]
	s_andn2_b64 vcc, exec, s[6:7]
	s_mov_b64 s[24:25], s[20:21]
	s_cbranch_vccnz .LBB0_3082
